# rec_pass1: LDS reads hoisted per straight-line (sub-)block everywhere (scores incl. j=0, chunk-state MFMA operands, P.V operands) on top of the batched prologue loops
# baseline (speedup 1.0000x reference)
.LBB0_196:
	s_or_b64 exec, exec, s[2:3]
	v_mul_u32_u24_e32 v4, 0x84, v114
	v_add3_u32 v6, v105, v104, v4
	ds_read2_b32 v[228:229], v6 offset1:33
	ds_read2_b32 v[230:231], v6 offset0:66 offset1:99
	ds_read2_b32 v[232:233], v6 offset0:132 offset1:165
	ds_read2_b32 v[234:235], v6 offset0:198 offset1:231
	s_movk_i32 s2, 0x90
	v_bfe_u32 v7, v111, 5, 3
	v_lshlrev_b32_e32 v8, 4, v7
	v_mul_u32_u24_e32 v7, 0x420, v7
	v_lshlrev_b32_e32 v15, 3, v112
	s_waitcnt lgkmcnt(0)
	v_pk_add_f32 v[228:229], v[106:107], v[228:229] op_sel_hi:[0,1]
	v_pk_add_f32 v[230:231], v[106:107], v[230:231] op_sel_hi:[0,1]
	v_pk_add_f32 v[232:233], v[106:107], v[232:233] op_sel_hi:[0,1]
	v_pk_add_f32 v[234:235], v[106:107], v[234:235] op_sel_hi:[0,1]
	ds_write2_b32 v6, v228, v229 offset1:33
	ds_write2_b32 v6, v230, v231 offset0:66 offset1:99
	ds_write2_b32 v6, v232, v233 offset0:132 offset1:165
	ds_write2_b32 v6, v234, v235 offset0:198 offset1:231
	v_and_b32_e32 v5, 31, v111
	v_lshlrev_b32_e32 v6, 2, v5
	v_add_u32_e32 v4, v105, v6
	s_waitcnt lgkmcnt(0)
	s_barrier
	ds_read_b32 v4, v4 offset:8316
	v_mad_u32_u24 v5, v5, s2, v105
	s_mov_b32 s2, 0xac00
	v_add3_u32 v5, v5, v8, s2
	v_add3_u32 v6, v105, v7, v6
	v_add_u32_e32 v199, 0x210, v6
	v_add_u32_e32 v200, 0x4400, v6
	v_add_u32_e32 v201, 0x4610, v6
	ds_read2_b32 v[236:237], v200 offset1:33
	ds_read2_b32 v[238:239], v6 offset1:33
	ds_read2_b32 v[240:241], v200 offset0:66 offset1:99
	ds_read2_b32 v[242:243], v6 offset0:66 offset1:99
	ds_read2_b32 v[244:245], v201 offset1:33
	ds_read2_b32 v[246:247], v199 offset1:33
	ds_read2_b32 v[248:249], v201 offset0:66 offset1:99
	ds_read2_b32 v[250:251], v199 offset0:66 offset1:99
	s_waitcnt lgkmcnt(0)
	v_sub_f32_e32 v238, v4, v238
	v_sub_f32_e32 v239, v4, v239
	v_sub_f32_e32 v242, v4, v242
	v_sub_f32_e32 v243, v4, v243
	v_mul_f32_e32 v238, 0x3fb8aa3b, v238
	v_mul_f32_e32 v239, 0x3fb8aa3b, v239
	v_mul_f32_e32 v242, 0x3fb8aa3b, v242
	v_mul_f32_e32 v243, 0x3fb8aa3b, v243
	v_exp_f32_e32 v238, v238
	v_exp_f32_e32 v239, v239
	v_exp_f32_e32 v242, v242
	v_exp_f32_e32 v243, v243
	s_nop 0
	v_mul_f32_e32 v238, v236, v238
	v_mul_f32_e32 v239, v237, v239
	v_mul_f32_e32 v242, v240, v242
	v_mul_f32_e32 v243, v241, v243
	v_cvt_pk_bf16_f32 v236, v238, v239
	v_cvt_pk_bf16_f32 v237, v242, v243
	ds_write_b64 v5, v[236:237]
	v_sub_f32_e32 v246, v4, v246
	v_sub_f32_e32 v247, v4, v247
	v_sub_f32_e32 v250, v4, v250
	v_sub_f32_e32 v251, v4, v251
	v_mul_f32_e32 v246, 0x3fb8aa3b, v246
	v_mul_f32_e32 v247, 0x3fb8aa3b, v247
	v_mul_f32_e32 v250, 0x3fb8aa3b, v250
	v_mul_f32_e32 v251, 0x3fb8aa3b, v251
	v_exp_f32_e32 v246, v246
	v_exp_f32_e32 v247, v247
	v_exp_f32_e32 v250, v250
	v_exp_f32_e32 v251, v251
	s_nop 0
	v_mul_f32_e32 v246, v244, v246
	v_mul_f32_e32 v247, v245, v247
	v_mul_f32_e32 v250, v248, v250
	v_mul_f32_e32 v251, v249, v251
	v_cvt_pk_bf16_f32 v244, v246, v247
	v_cvt_pk_bf16_f32 v245, v250, v251
	ds_write_b64 v5, v[244:245] offset:8
	v_lshl_add_u32 v8, v15, 1, v105
	s_movk_i32 s2, 0x90
	v_mad_u32_u24 v12, v110, s2, v8
	s_waitcnt lgkmcnt(0)
	s_barrier
	ds_read_b128 v[4:7], v12 offset:34816
	v_mad_u32_u24 v13, v107, s2, v8
	ds_read_b128 v[200:203], v13 offset:44032
	ds_read_b128 v[220:223], v13 offset:46336
	ds_read_b128 v[224:227], v12 offset:34880
	ds_read_b128 v[228:231], v13 offset:46400
	ds_read_b128 v[232:235], v13 offset:44096
	s_waitcnt lgkmcnt(3)
	v_mfma_f32_16x16x32_bf16 v[8:11], v[200:203], v[4:7], 0
	v_ashrrev_i32_e32 v103, 31, v102
	v_readlane_b32 s2, v254, 17
	v_readlane_b32 s3, v254, 18
	s_waitcnt lgkmcnt(2)
	v_mfma_f32_16x16x32_bf16 v[4:7], v[220:223], v[4:7], 0
	v_mov_b32_e32 v13, v177
	v_cmp_lt_u32_sdwa s[4:5], v111, v218 src0_sel:BYTE_0 src1_sel:DWORD
	s_waitcnt lgkmcnt(1)
	v_mfma_f32_16x16x32_bf16 v[4:7], v[228:231], v[224:227], v[4:7]
	v_lshlrev_b32_e32 v24, 2, v112
	s_waitcnt lgkmcnt(0)
	v_mfma_f32_16x16x32_bf16 v[16:19], v[232:235], v[224:227], v[8:11]
	s_nop 2
	v_or_b32_e32 v198, v113, v107
	v_lshl_or_b32 v198, v198, 5, v24
	v_lshlrev_b32_e32 v196, 2, v198
	v_mov_b32_e32 v197, v177
	v_or_b32_e32 v11, v113, v24
	v_lshlrev_b32_e32 v11, 5, v11
	v_lshlrev_b64 v[8:9], 13, v[102:103]
	v_or_b32_e32 v12, v11, v107
	v_lshl_add_u64 v[8:9], s[2:3], 0, v[8:9]
	v_lshl_add_u64 v[196:197], v[8:9], 0, v[196:197]
	v_lshlrev_b32_e32 v12, 2, v12
	v_or_b32_e32 v10, 16, v107
	v_lshl_add_u64 v[12:13], v[8:9], 0, v[12:13]
	global_store_dwordx4 v[196:197], v[16:19], off sc1
	global_store_dwordx4 v[196:197], v[4:7], off offset:64 sc1
	s_nop 1
	v_or_b32_e32 v4, v11, v10
	v_lshlrev_b32_e32 v12, 2, v4
	v_mov_b32_e32 v13, v177
	v_lshl_add_u64 v[8:9], v[8:9], 0, v[12:13]
	s_waitcnt lgkmcnt(0)
	v_mov_b32_e32 v20, v224
	v_mov_b32_e32 v21, v225
	v_mov_b32_e32 v22, v226
	v_mov_b32_e32 v23, v227
	v_mov_b32_e32 v25, v229
	v_mov_b32_e32 v26, v230
	v_mov_b32_e32 v27, v231
	s_and_saveexec_b64 s[2:3], s[4:5]
	s_cbranch_execz .LBB0_200
	v_lshlrev_b32_sdwa v4, v213, v111 dst_sel:DWORD dst_unused:UNUSED_PAD src0_sel:DWORD src1_sel:BYTE_0
	v_add_u32_e32 v5, v105, v4
	ds_read_b32 v5, v5 offset:8316
	v_readlane_b32 s4, v254, 19
	v_lshlrev_b64 v[6:7], 7, v[102:103]
	v_readlane_b32 s5, v254, 20
	s_waitcnt lgkmcnt(0)
	v_mul_f32_e32 v5, 0x3fb8aa3b, v5
	v_exp_f32_e32 v8, v5
	v_lshl_add_u64 v[6:7], s[4:5], 0, v[6:7]
	v_mov_b32_e32 v5, v177
	v_lshl_add_u64 v[4:5], v[6:7], 0, v[4:5]
	global_store_dword v[4:5], v8, off
.LBB0_200:
	s_or_b64 exec, exec, s[2:3]
	s_movk_i32 s2, 0x840
	v_mad_u32_u24 v12, v108, s2, v105
	v_add_u32_e32 v4, 0xffffff7c, v12
	v_cmp_eq_u32_e64 s[36:37], 0, v108
	v_cmp_ne_u32_e32 vcc, 0, v108
	v_mov_b32_e32 v25, 0
	v_lshl_add_u32 v14, v15, 2, v4
	v_mov_b32_e32 v26, 0
	s_and_saveexec_b64 s[2:3], vcc
	ds_read_b32 v26, v14
	s_or_b64 exec, exec, s[2:3]
	v_lshlrev_b32_e32 v13, 2, v15
	s_and_saveexec_b64 s[2:3], vcc
	s_movk_i32 s4, 0xff80
	v_add3_u32 v4, v12, v13, s4
	ds_read_b32 v25, v4
	s_or_b64 exec, exec, s[2:3]
	v_mul_u32_u24_e32 v4, 0x84, v110
	v_add3_u32 v11, v105, v4, v13
	ds_read2_b32 v[4:5], v11 offset1:1
	v_mov_b32_e32 v27, 0
	v_mov_b32_e32 v28, 0
	s_and_saveexec_b64 s[2:3], vcc
	ds_read_b32 v28, v14 offset:8
	s_or_b64 exec, exec, s[2:3]
	s_and_saveexec_b64 s[2:3], vcc
	s_movk_i32 s4, 0xff88
	v_add3_u32 v6, v12, v13, s4
	ds_read_b32 v27, v6
	s_or_b64 exec, exec, s[2:3]
	ds_read2_b32 v[6:7], v11 offset0:2 offset1:3
	v_mov_b32_e32 v20, 0
	v_mov_b32_e32 v21, 0
	s_and_saveexec_b64 s[2:3], vcc
	ds_read_b32 v21, v14 offset:16
	s_or_b64 exec, exec, s[2:3]
	s_and_saveexec_b64 s[2:3], vcc
	s_movk_i32 s4, 0xff90
	v_add3_u32 v8, v12, v13, s4
	ds_read_b32 v20, v8
	s_or_b64 exec, exec, s[2:3]
	ds_read2_b32 v[8:9], v11 offset0:4 offset1:5
	v_mov_b32_e32 v22, 0
	v_mov_b32_e32 v23, 0
	s_and_saveexec_b64 s[2:3], vcc
	ds_read_b32 v23, v14 offset:24
	s_or_b64 exec, exec, s[2:3]
	s_and_saveexec_b64 s[2:3], vcc
	s_movk_i32 s4, 0xff98
	v_add3_u32 v12, v12, v13, s4
	ds_read_b32 v22, v12
	s_or_b64 exec, exec, s[2:3]
	s_waitcnt lgkmcnt(2)
	v_sub_f32_e32 v12, v4, v26
	v_sub_f32_e32 v13, v5, v25
	v_mul_f32_e32 v4, 0x3fb8aa3b, v4
	v_mul_f32_e32 v5, 0x3fb8aa3b, v5
	v_exp_f32_e32 v4, v4
	v_exp_f32_e32 v5, v5
	v_mul_f32_e32 v12, 0x3fb8aa3b, v12
	v_mul_f32_e32 v13, 0x3fb8aa3b, v13
	v_exp_f32_e32 v12, v12
	v_exp_f32_e32 v13, v13
	v_lshlrev_b32_e32 v16, 16, v0
	v_and_b32_e32 v17, 0xffff0000, v0
	s_mov_b32 s2, 0x3e3504f3
	v_pk_mul_f32 v[16:17], v[16:17], s[2:3] op_sel_hi:[1,0]
	s_movk_i32 s4, 0x300
	v_pk_mul_f32 v[4:5], v[16:17], v[4:5]
	v_pk_mul_f32 v[12:13], v[16:17], v[12:13]
	v_cvt_pk_bf16_f32 v4, v4, v5
	s_waitcnt lgkmcnt(1)
	v_sub_f32_e32 v5, v6, v28
	v_mul_f32_e32 v5, 0x3fb8aa3b, v5
	v_cvt_pk_bf16_f32 v0, v12, v13
	v_exp_f32_e32 v12, v5
	v_sub_f32_e32 v5, v7, v27
	v_mul_f32_e32 v5, 0x3fb8aa3b, v5
	v_exp_f32_e32 v13, v5
	v_mul_f32_e32 v5, 0x3fb8aa3b, v6
	v_exp_f32_e32 v6, v5
	v_mul_f32_e32 v5, 0x3fb8aa3b, v7
	v_exp_f32_e32 v7, v5
	v_lshlrev_b32_e32 v16, 16, v1
	v_and_b32_e32 v17, 0xffff0000, v1
	v_pk_mul_f32 v[16:17], v[16:17], s[2:3] op_sel_hi:[1,0]
	v_or_b32_e32 v31, 2, v24
	v_pk_mul_f32 v[6:7], v[16:17], v[6:7]
	v_pk_mul_f32 v[12:13], v[16:17], v[12:13]
	v_cvt_pk_bf16_f32 v5, v6, v7
	s_waitcnt lgkmcnt(0)
	v_sub_f32_e32 v6, v8, v21
	v_sub_f32_e32 v7, v9, v20
	v_mul_f32_e32 v6, 0x3fb8aa3b, v6
	v_mul_f32_e32 v7, 0x3fb8aa3b, v7
	v_exp_f32_e32 v6, v6
	v_exp_f32_e32 v7, v7
	v_mul_f32_e32 v8, 0x3fb8aa3b, v8
	v_mul_f32_e32 v9, 0x3fb8aa3b, v9
	v_exp_f32_e32 v8, v8
	v_exp_f32_e32 v9, v9
	v_cvt_pk_bf16_f32 v1, v12, v13
	v_lshlrev_b32_e32 v12, 16, v2
	v_and_b32_e32 v13, 0xffff0000, v2
	v_pk_mul_f32 v[12:13], v[12:13], s[2:3] op_sel_hi:[1,0]
	v_lshlrev_b32_e32 v16, 16, v3
	v_pk_mul_f32 v[6:7], v[12:13], v[6:7]
	v_and_b32_e32 v17, 0xffff0000, v3
	v_cvt_pk_bf16_f32 v2, v6, v7
	v_pk_mul_f32 v[6:7], v[12:13], v[8:9]
	ds_read2_b32 v[8:9], v11 offset0:6 offset1:7
	v_cvt_pk_bf16_f32 v6, v6, v7
	v_pk_mul_f32 v[16:17], v[16:17], s[2:3] op_sel_hi:[1,0]
	v_or_b32_e32 v30, 3, v24
	s_waitcnt lgkmcnt(0)
	v_sub_f32_e32 v7, v8, v23
	v_mul_f32_e32 v7, 0x3fb8aa3b, v7
	v_exp_f32_e32 v12, v7
	v_sub_f32_e32 v7, v9, v22
	v_mul_f32_e32 v7, 0x3fb8aa3b, v7
	v_exp_f32_e32 v13, v7
	v_mul_f32_e32 v7, 0x3fb8aa3b, v8
	v_exp_f32_e32 v8, v7
	v_mul_f32_e32 v7, 0x3fb8aa3b, v9
	v_exp_f32_e32 v9, v7
	v_pk_mul_f32 v[12:13], v[16:17], v[12:13]
	v_pk_mul_f32 v[8:9], v[16:17], v[8:9]
	s_nop 0
	v_cvt_pk_bf16_f32 v7, v8, v9
	v_mov_b64_e32 v[8:9], s[68:69]
	v_mad_u64_u32 v[8:9], s[2:3], v100, s4, v[8:9]
	v_cvt_pk_bf16_f32 v3, v12, v13
	v_mov_b32_e32 v12, v9
	v_mad_u64_u32 v[12:13], s[2:3], v101, s4, v[12:13]
	v_mov_b32_e32 v9, v12
	v_lshlrev_b32_e32 v12, 1, v109
	v_mov_b32_e32 v13, v177
	v_lshl_add_u64 v[8:9], v[8:9], 0, v[12:13]
	v_lshlrev_b32_e32 v12, 1, v15
	v_lshl_add_u64 v[8:9], v[8:9], 0, v[12:13]
	s_mov_b32 s2, 0xece4000
	v_add_co_u32_e64 v8, s[38:39], s2, v8
	s_nop 1
	v_addc_co_u32_e64 v9, s[38:39], 0, v9, s[38:39]
	global_store_dwordx4 v[8:9], v[4:7], off offset:512 sc1
	s_nop 1
	v_mad_u32_u24 v4, v107, 33, v15
	v_lshl_add_u32 v29, v4, 2, v105
	ds_read2_b32 v[200:201], v29 offset1:1
	v_add_u32_e32 v199, 0x4400, v29
	ds_read2_b32 v[202:203], v199 offset1:1
	ds_read2_b32 v[204:205], v29 offset0:2 offset1:3
	v_add_u32_e32 v222, 0x4408, v29
	ds_read2_b32 v[220:221], v222 offset1:1
	ds_read2_b32 v[224:225], v29 offset0:4 offset1:5
	v_add_u32_e32 v223, 0x4410, v29
	ds_read2_b32 v[226:227], v223 offset1:1
	ds_read2_b32 v[228:229], v29 offset0:6 offset1:7
	v_add_u32_e32 v232, 0x4418, v29
	ds_read2_b32 v[230:231], v232 offset1:1
	v_add_u32_e32 v6, 0x4400, v29
	s_waitcnt lgkmcnt(1)
	v_sub_f32_e32 v4, v26, v200
	v_sub_f32_e32 v5, v25, v201
	v_min_f32_e32 v4, 0x42a00000, v4
	v_min_f32_e32 v5, 0x42a00000, v5
	v_mul_f32_e32 v4, 0x3fb8aa3b, v4
	v_mul_f32_e32 v5, 0x3fb8aa3b, v5
	v_exp_f32_e32 v4, v4
	v_exp_f32_e32 v5, v5
	s_waitcnt lgkmcnt(0)
	v_pk_mul_f32 v[4:5], v[202:203], v[4:5]
	v_cvt_pk_bf16_f32 v4, v4, v5
	v_add_u32_e32 v5, 0x4408, v29
	s_waitcnt lgkmcnt(1)
	v_sub_f32_e32 v6, v28, v204
	v_sub_f32_e32 v7, v27, v205
	v_min_f32_e32 v6, 0x42a00000, v6
	v_min_f32_e32 v7, 0x42a00000, v7
	v_mul_f32_e32 v6, 0x3fb8aa3b, v6
	v_mul_f32_e32 v7, 0x3fb8aa3b, v7
	v_exp_f32_e32 v6, v6
	v_exp_f32_e32 v7, v7
	s_waitcnt lgkmcnt(0)
	v_pk_mul_f32 v[6:7], v[220:221], v[6:7]
	s_nop 0
	v_cvt_pk_bf16_f32 v5, v6, v7
	v_add_u32_e32 v8, 0x4410, v29
	s_waitcnt lgkmcnt(1)
	v_sub_f32_e32 v6, v21, v224
	v_sub_f32_e32 v7, v20, v225
	v_min_f32_e32 v6, 0x42a00000, v6
	v_min_f32_e32 v7, 0x42a00000, v7
	v_mul_f32_e32 v6, 0x3fb8aa3b, v6
	v_mul_f32_e32 v7, 0x3fb8aa3b, v7
	v_exp_f32_e32 v6, v6
	v_exp_f32_e32 v7, v7
	s_waitcnt lgkmcnt(0)
	v_pk_mul_f32 v[6:7], v[226:227], v[6:7]
	v_cvt_pk_bf16_f32 v6, v6, v7
	v_add_u32_e32 v7, 0x4418, v29
	s_waitcnt lgkmcnt(1)
	v_sub_f32_e32 v8, v23, v228
	v_sub_f32_e32 v9, v22, v229
	v_min_f32_e32 v8, 0x42a00000, v8
	v_min_f32_e32 v9, 0x42a00000, v9
	v_mul_f32_e32 v8, 0x3fb8aa3b, v8
	v_mul_f32_e32 v9, 0x3fb8aa3b, v9
	v_exp_f32_e32 v8, v8
	v_exp_f32_e32 v9, v9
	s_waitcnt lgkmcnt(0)
	v_pk_mul_f32 v[8:9], v[230:231], v[8:9]
	s_nop 0
	v_cvt_pk_bf16_f32 v7, v8, v9
	v_mov_b32_e32 v8, 0
	s_nop 0
	v_mfma_f32_16x16x32_bf16 v[4:7], v[4:7], v[0:3], 0
	s_waitcnt lgkmcnt(0)
	v_mov_b32_e32 v12, v230
	v_mov_b32_e32 v13, v231
	s_and_saveexec_b64 s[2:3], s[36:37]
	v_cmp_gt_u32_e64 s[36:37], v24, v107
	s_nop 5
	v_cndmask_b32_e64 v9, v4, 0, s[36:37]
	v_cmp_lt_u32_e64 s[36:37], v24, v107
	s_nop 1
	v_cndmask_b32_e64 v4, v9, v4, s[36:37]
	v_cndmask_b32_e64 v5, 0, v5, s[36:37]
	v_cmp_le_u32_e64 s[36:37], v31, v107
	s_nop 1
	v_cndmask_b32_e64 v6, 0, v6, s[36:37]
	v_cmp_le_u32_e64 s[36:37], v30, v107
	s_nop 1
	v_cndmask_b32_e64 v7, 0, v7, s[36:37]
	s_or_b64 exec, exec, s[2:3]
	v_mov_b32_e32 v16, 0
	v_mov_b32_e32 v17, 0
	v_mov_b32_e32 v18, 0
	v_mov_b32_e32 v19, 0
	s_and_saveexec_b64 s[4:5], vcc
	s_cbranch_execz .LBB0_222
	v_mad_u32_u24 v9, v10, 33, v15
	v_lshl_add_u32 v9, v9, 2, v105
	ds_read2_b32 v[200:201], v9 offset1:1
	v_add_u32_e32 v199, 0x4400, v9
	ds_read2_b32 v[202:203], v199 offset1:1
	ds_read2_b32 v[204:205], v9 offset0:2 offset1:3
	v_add_u32_e32 v222, 0x4408, v9
	ds_read2_b32 v[220:221], v222 offset1:1
	ds_read2_b32 v[224:225], v9 offset0:4 offset1:5
	v_add_u32_e32 v223, 0x4410, v9
	ds_read2_b32 v[226:227], v223 offset1:1
	ds_read2_b32 v[228:229], v9 offset0:6 offset1:7
	v_add_u32_e32 v232, 0x4418, v9
	ds_read2_b32 v[230:231], v232 offset1:1
	v_add_u32_e32 v12, 0x4400, v9
	v_add_u32_e32 v14, 0x4410, v9
	v_cmp_eq_u32_e32 vcc, 1, v108
	s_waitcnt lgkmcnt(1)
	v_sub_f32_e32 v10, v26, v200
	v_sub_f32_e32 v11, v25, v201
	v_min_f32_e32 v10, 0x42a00000, v10
	v_min_f32_e32 v11, 0x42a00000, v11
	v_mul_f32_e32 v10, 0x3fb8aa3b, v10
	v_mul_f32_e32 v11, 0x3fb8aa3b, v11
	v_exp_f32_e32 v10, v10
	v_exp_f32_e32 v11, v11
	s_waitcnt lgkmcnt(0)
	v_pk_mul_f32 v[10:11], v[202:203], v[10:11]
	v_cvt_pk_bf16_f32 v10, v10, v11
	v_add_u32_e32 v11, 0x4408, v9
	s_waitcnt lgkmcnt(1)
	v_sub_f32_e32 v12, v28, v204
	v_sub_f32_e32 v13, v27, v205
	v_min_f32_e32 v12, 0x42a00000, v12
	v_min_f32_e32 v13, 0x42a00000, v13
	v_mul_f32_e32 v12, 0x3fb8aa3b, v12
	v_mul_f32_e32 v13, 0x3fb8aa3b, v13
	v_exp_f32_e32 v12, v12
	v_exp_f32_e32 v13, v13
	s_waitcnt lgkmcnt(0)
	v_pk_mul_f32 v[12:13], v[220:221], v[12:13]
	s_nop 0
	v_cvt_pk_bf16_f32 v11, v12, v13
	s_waitcnt lgkmcnt(1)
	v_sub_f32_e32 v12, v21, v224
	v_sub_f32_e32 v13, v20, v225
	v_min_f32_e32 v12, 0x42a00000, v12
	v_min_f32_e32 v13, 0x42a00000, v13
	v_mul_f32_e32 v12, 0x3fb8aa3b, v12
	v_mul_f32_e32 v13, 0x3fb8aa3b, v13
	v_exp_f32_e32 v12, v12
	v_exp_f32_e32 v13, v13
	s_waitcnt lgkmcnt(0)
	v_pk_mul_f32 v[12:13], v[226:227], v[12:13]
	v_cvt_pk_bf16_f32 v12, v12, v13
	v_add_u32_e32 v13, 0x4418, v9
	s_waitcnt lgkmcnt(1)
	v_sub_f32_e32 v9, v23, v228
	v_min_f32_e32 v9, 0x42a00000, v9
	v_mul_f32_e32 v9, 0x3fb8aa3b, v9
	v_exp_f32_e32 v16, v9
	v_sub_f32_e32 v9, v22, v229
	v_min_f32_e32 v9, 0x42a00000, v9
	v_mul_f32_e32 v9, 0x3fb8aa3b, v9
	v_exp_f32_e32 v17, v9
	s_waitcnt lgkmcnt(0)
	v_pk_mul_f32 v[16:17], v[230:231], v[16:17]
	s_nop 0
	v_cvt_pk_bf16_f32 v13, v16, v17
	s_nop 1
	v_mfma_f32_16x16x32_bf16 v[16:19], v[10:13], v[0:3], 0
	s_and_saveexec_b64 s[2:3], vcc
	s_cbranch_execz .LBB0_221
	v_cmp_gt_u32_e32 vcc, v24, v107
	s_nop 4
	v_cndmask_b32_e32 v9, v18, v18, vcc
	v_cndmask_b32_e32 v10, v19, v19, vcc
	v_cndmask_b32_e64 v11, v16, 0, vcc
	v_cmp_lt_u32_e32 vcc, v24, v107
	s_nop 1
	v_cndmask_b32_e32 v16, v11, v16, vcc
	v_cndmask_b32_e32 v10, v10, v19, vcc
	v_cndmask_b32_e32 v9, v9, v18, vcc
	v_cndmask_b32_e32 v17, 0, v17, vcc
	v_cmp_le_u32_e32 vcc, v31, v107
	s_nop 1
	v_cndmask_b32_e32 v18, 0, v9, vcc
	v_cmp_le_u32_e32 vcc, v30, v107
	s_nop 1
	v_cndmask_b32_e32 v19, 0, v10, vcc

.LBB0_222:
	s_or_b64 exec, exec, s[4:5]
	v_cmp_lt_u32_e32 vcc, 1, v108
	v_mov_b32_e32 v9, 0
	v_mov_b32_e32 v10, 0
	v_mov_b32_e32 v11, 0
	s_and_saveexec_b64 s[4:5], vcc
	s_cbranch_execz .LBB0_226
	v_add_u32_e32 v8, 0x1080, v29
	ds_read2_b32 v[200:201], v8 offset1:1
	v_add_u32_e32 v199, 0x5480, v29
	ds_read2_b32 v[202:203], v199 offset1:1
	v_add_u32_e32 v220, 0x1088, v29
	ds_read2_b32 v[204:205], v220 offset1:1
	v_add_u32_e32 v221, 0x5488, v29
	ds_read2_b32 v[222:223], v221 offset1:1
	v_add_u32_e32 v226, 0x1090, v29
	ds_read2_b32 v[224:225], v226 offset1:1
	v_add_u32_e32 v227, 0x5490, v29
	ds_read2_b32 v[228:229], v227 offset1:1
	v_add_u32_e32 v232, 0x1098, v29
	ds_read2_b32 v[230:231], v232 offset1:1
	v_add_u32_e32 v233, 0x5498, v29
	ds_read2_b32 v[234:235], v233 offset1:1
	v_add_u32_e32 v10, 0x5480, v29
	v_cmp_eq_u32_e64 s[36:37], 2, v108
	s_waitcnt lgkmcnt(1)
	v_sub_f32_e32 v8, v26, v200
	v_sub_f32_e32 v9, v25, v201
	v_min_f32_e32 v8, 0x42a00000, v8
	v_min_f32_e32 v9, 0x42a00000, v9
	v_mul_f32_e32 v8, 0x3fb8aa3b, v8
	v_mul_f32_e32 v9, 0x3fb8aa3b, v9
	v_exp_f32_e32 v8, v8
	v_exp_f32_e32 v9, v9
	s_waitcnt lgkmcnt(0)
	v_pk_mul_f32 v[8:9], v[202:203], v[8:9]
	s_nop 0
	v_cvt_pk_bf16_f32 v8, v8, v9
	v_add_u32_e32 v9, 0x1088, v29
	s_waitcnt lgkmcnt(0)
	v_sub_f32_e32 v9, v28, v204
	v_min_f32_e32 v9, 0x42a00000, v9
	v_mul_f32_e32 v9, 0x3fb8aa3b, v9
	v_exp_f32_e32 v10, v9
	v_sub_f32_e32 v9, v27, v205
	v_min_f32_e32 v9, 0x42a00000, v9
	v_mul_f32_e32 v9, 0x3fb8aa3b, v9
	v_exp_f32_e32 v11, v9
	v_add_u32_e32 v9, 0x5488, v29
	s_waitcnt lgkmcnt(0)
	v_pk_mul_f32 v[10:11], v[222:223], v[10:11]
	s_nop 0
	v_cvt_pk_bf16_f32 v9, v10, v11
	v_add_u32_e32 v10, 0x1090, v29
	v_add_u32_e32 v12, 0x5490, v29
	s_waitcnt lgkmcnt(1)
	v_sub_f32_e32 v10, v21, v224
	v_sub_f32_e32 v11, v20, v225
	v_min_f32_e32 v10, 0x42a00000, v10
	v_min_f32_e32 v11, 0x42a00000, v11
	v_mul_f32_e32 v10, 0x3fb8aa3b, v10
	v_mul_f32_e32 v11, 0x3fb8aa3b, v11
	v_exp_f32_e32 v10, v10
	v_exp_f32_e32 v11, v11
	s_waitcnt lgkmcnt(0)
	v_pk_mul_f32 v[10:11], v[228:229], v[10:11]
	s_nop 0
	v_cvt_pk_bf16_f32 v10, v10, v11
	v_add_u32_e32 v11, 0x1098, v29
	s_waitcnt lgkmcnt(0)
	v_sub_f32_e32 v11, v23, v230
	v_min_f32_e32 v11, 0x42a00000, v11
	v_mul_f32_e32 v11, 0x3fb8aa3b, v11
	v_exp_f32_e32 v12, v11
	v_sub_f32_e32 v11, v22, v231
	v_min_f32_e32 v11, 0x42a00000, v11
	v_mul_f32_e32 v11, 0x3fb8aa3b, v11
	v_exp_f32_e32 v13, v11
	v_add_u32_e32 v11, 0x5498, v29
	s_waitcnt lgkmcnt(0)
	v_pk_mul_f32 v[12:13], v[234:235], v[12:13]
	s_nop 0
	v_cvt_pk_bf16_f32 v11, v12, v13
	s_nop 1
	v_mfma_f32_16x16x32_bf16 v[8:11], v[8:11], v[0:3], 0
	s_waitcnt lgkmcnt(0)
	v_mov_b32_e32 v32, v234
	v_mov_b32_e32 v33, v235
	s_and_saveexec_b64 s[2:3], s[36:37]
	s_cbranch_execz .LBB0_225
	v_cmp_gt_u32_e64 s[36:37], v24, v107
	s_nop 4
	v_cndmask_b32_e64 v12, v10, v10, s[36:37]
	v_cndmask_b32_e64 v13, v11, v11, s[36:37]
	v_cndmask_b32_e64 v14, v8, 0, s[36:37]
	v_cmp_lt_u32_e64 s[36:37], v24, v107
	s_nop 1
	v_cndmask_b32_e64 v8, v14, v8, s[36:37]
	v_cndmask_b32_e64 v11, v13, v11, s[36:37]
	v_cndmask_b32_e64 v10, v12, v10, s[36:37]
	v_cndmask_b32_e64 v9, 0, v9, s[36:37]
	v_cmp_le_u32_e64 s[36:37], v31, v107
	s_nop 1
	v_cndmask_b32_e64 v10, 0, v10, s[36:37]
	v_cmp_le_u32_e64 s[36:37], v30, v107
	s_nop 1
	v_cndmask_b32_e64 v11, 0, v11, s[36:37]

.LBB0_226:
	s_or_b64 exec, exec, s[4:5]
	v_cmp_eq_u32_e64 s[36:37], 3, v108
	v_mov_b32_e32 v12, 0
	v_mov_b32_e32 v13, 0
	v_mov_b32_e32 v14, 0
	v_mov_b32_e32 v32, 0
	s_and_saveexec_b64 s[4:5], s[36:37]
	s_cbranch_execz .LBB0_228
	v_add_u32_e32 v12, 0x18c0, v29
	v_add_u32_e32 v32, 0x18c8, v29
	v_add_u32_e32 v34, 0x5cc8, v29
	v_add_u32_e32 v14, 0x5cc0, v29
	ds_read2_b32 v[200:201], v12 offset1:1
	ds_read2_b32 v[202:203], v32 offset1:1
	ds_read2_b32 v[204:205], v34 offset1:1
	ds_read2_b32 v[220:221], v14 offset1:1
	v_add_u32_e32 v199, 0x18d0, v29
	ds_read2_b32 v[222:223], v199 offset1:1
	v_add_u32_e32 v226, 0x5cd0, v29
	ds_read2_b32 v[224:225], v226 offset1:1
	v_add_u32_e32 v227, 0x18d8, v29
	ds_read2_b32 v[228:229], v227 offset1:1
	v_add_u32_e32 v232, 0x5cd8, v29
	ds_read2_b32 v[230:231], v232 offset1:1
	v_cmp_lt_u32_e64 s[36:37], v24, v107
	s_waitcnt lgkmcnt(2)
	v_sub_f32_e32 v14, v28, v202
	v_min_f32_e32 v14, 0x42a00000, v14
	v_sub_f32_e32 v12, v26, v200
	v_sub_f32_e32 v13, v25, v201
	v_mul_f32_e32 v14, 0x3fb8aa3b, v14
	v_min_f32_e32 v12, 0x42a00000, v12
	v_min_f32_e32 v13, 0x42a00000, v13
	v_exp_f32_e32 v32, v14
	v_sub_f32_e32 v14, v27, v203
	v_mul_f32_e32 v12, 0x3fb8aa3b, v12
	v_mul_f32_e32 v13, 0x3fb8aa3b, v13
	v_min_f32_e32 v14, 0x42a00000, v14
	v_exp_f32_e32 v12, v12
	v_exp_f32_e32 v13, v13
	v_mul_f32_e32 v14, 0x3fb8aa3b, v14
	v_exp_f32_e32 v33, v14
	v_add_u32_e32 v14, 0x18d0, v29
	s_waitcnt lgkmcnt(0)
	v_pk_mul_f32 v[12:13], v[220:221], v[12:13]
	v_add_u32_e32 v25, 0x18d8, v29
	v_cvt_pk_bf16_f32 v26, v12, v13
	v_pk_mul_f32 v[12:13], v[204:205], v[32:33]
	v_add_u32_e32 v14, 0x5cd0, v29
	v_add_u32_e32 v27, 0x5cd8, v29
	v_cvt_pk_bf16_f32 v27, v12, v13
	s_waitcnt lgkmcnt(3)
	v_sub_f32_e32 v14, v21, v222
	v_min_f32_e32 v14, 0x42a00000, v14
	v_mul_f32_e32 v14, 0x3fb8aa3b, v14
	v_exp_f32_e32 v32, v14
	v_sub_f32_e32 v14, v20, v223
	v_min_f32_e32 v14, 0x42a00000, v14
	v_mul_f32_e32 v14, 0x3fb8aa3b, v14
	v_exp_f32_e32 v33, v14
	s_waitcnt lgkmcnt(1)
	v_sub_f32_e32 v14, v23, v228
	v_min_f32_e32 v14, 0x42a00000, v14
	v_mul_f32_e32 v14, 0x3fb8aa3b, v14
	v_exp_f32_e32 v20, v14
	v_sub_f32_e32 v14, v22, v229
	v_min_f32_e32 v14, 0x42a00000, v14
	v_mul_f32_e32 v14, 0x3fb8aa3b, v14
	v_exp_f32_e32 v21, v14
	v_pk_mul_f32 v[12:13], v[224:225], v[32:33]
	s_nop 0
	v_cvt_pk_bf16_f32 v28, v12, v13
	s_waitcnt lgkmcnt(0)
	v_pk_mul_f32 v[12:13], v[230:231], v[20:21]
	s_nop 0
	v_cvt_pk_bf16_f32 v29, v12, v13
	s_nop 1
	v_mfma_f32_16x16x32_bf16 v[0:3], v[26:29], v[0:3], 0
	s_nop 7
	v_cndmask_b32_e64 v13, 0, v1, s[36:37]
	v_cmp_le_u32_e64 s[36:37], v24, v107
	s_nop 1
	v_cndmask_b32_e64 v12, 0, v0, s[36:37]
	v_cmp_le_u32_e64 s[36:37], v31, v107
	s_nop 1
	v_cndmask_b32_e64 v14, 0, v2, s[36:37]
	v_cmp_le_u32_e64 s[36:37], v30, v107
	s_nop 1
	v_cndmask_b32_e64 v32, 0, v3, s[36:37]
	s_waitcnt lgkmcnt(0)
	v_mov_b32_e32 v34, v228
	v_mov_b32_e32 v35, v229
	v_mov_b32_e32 v36, v230
	v_mov_b32_e32 v37, v231
.LBB0_228:
	s_or_b64 exec, exec, s[4:5]
	v_mul_u32_u24_e32 v0, 0x90, v107
	v_add_u32_e32 v1, v105, v15
	v_add_u32_e32 v26, v1, v0
	v_add_u32_e32 v27, 0x8800, v26
	ds_read2_b64 v[200:203], v27 offset1:4
	v_add_u32_e32 v199, 0x9000, v26
	ds_read2_b64 v[220:223], v199 offset0:32 offset1:36
	v_add_u32_e32 v204, 0x9800, v26
	ds_read2_b64 v[224:227], v204 offset0:64 offset1:68
	v_add_u32_e32 v205, 0xa000, v26
	ds_read2_b64 v[228:231], v205 offset0:96 offset1:100
	v_cvt_pk_bf16_f32 v20, v4, v5
	v_cvt_pk_bf16_f32 v21, v6, v7
	v_cvt_pk_bf16_f32 v22, v16, v17
	v_cvt_pk_bf16_f32 v23, v18, v19
	v_add_u32_e32 v15, 0x9000, v26
	v_add_u32_e32 v25, 0x9800, v26
	v_add_u32_e32 v26, 0xa000, v26
	s_waitcnt lgkmcnt(0)
	v_mfma_f32_16x16x32_bf16 v[4:7], v[200:203], v[20:23], 0
	s_waitcnt lgkmcnt(1)
	v_mfma_f32_16x16x32_bf16 v[16:19], v[224:227], v[20:23], 0
	v_mfma_f32_16x16x32_bf16 v[0:3], v[220:223], v[20:23], 0
	s_waitcnt lgkmcnt(0)
	v_mfma_f32_16x16x32_bf16 v[20:23], v[228:231], v[20:23], 0
	s_waitcnt lgkmcnt(0)
	v_mov_b32_e32 v28, v228
	v_mov_b32_e32 v29, v229
	v_mov_b32_e32 v30, v230
	v_mov_b32_e32 v31, v231
	s_and_saveexec_b64 s[2:3], vcc
	s_cbranch_execz .LBB0_230
	v_cvt_pk_bf16_f32 v8, v8, v9
	v_cvt_pk_bf16_f32 v9, v10, v11
	v_cvt_pk_bf16_f32 v10, v12, v13
	v_cvt_pk_bf16_f32 v11, v14, v32
	ds_read2_b64 v[200:203], v15 offset0:40 offset1:44
	ds_read2_b64 v[220:223], v27 offset0:8 offset1:12
	ds_read2_b64 v[224:227], v25 offset0:72 offset1:76
	ds_read2_b64 v[228:231], v26 offset0:104 offset1:108
	s_waitcnt lgkmcnt(1)
	v_mfma_f32_16x16x32_bf16 v[0:3], v[200:203], v[8:11], v[0:3]
	s_waitcnt lgkmcnt(1)
	v_mfma_f32_16x16x32_bf16 v[4:7], v[220:223], v[8:11], v[4:7]
	s_waitcnt lgkmcnt(0)
	v_mfma_f32_16x16x32_bf16 v[16:19], v[224:227], v[8:11], v[16:19]
	s_waitcnt lgkmcnt(0)
	v_mfma_f32_16x16x32_bf16 v[20:23], v[228:231], v[8:11], v[20:23]
	s_waitcnt lgkmcnt(0)
	v_mov_b32_e32 v12, v228
	v_mov_b32_e32 v13, v229
	v_mov_b32_e32 v14, v230
	v_mov_b32_e32 v15, v231
	v_mov_b32_e32 v28, v220
	v_mov_b32_e32 v29, v221
	v_mov_b32_e32 v30, v222
	v_mov_b32_e32 v31, v223

.LBB0_238:
	s_or_b64 exec, exec, s[2:3]
	v_lshlrev_b32_e32 v29, 3, v23
	v_lshl_add_u32 v8, v21, 2, v28
	v_mov_b32_e32 v21, v20
	v_mad_u32_u24 v30, v18, s14, v8
	ds_read_b32 v80, v30
	ds_read_b32 v81, v30 offset:260
	ds_read_b32 v82, v30 offset:520
	ds_read_b32 v83, v30 offset:780
	ds_read_b32 v84, v30 offset:1040
	ds_read_b32 v85, v30 offset:1300
	ds_read_b32 v86, v30 offset:1560
	ds_read_b32 v87, v30 offset:1820
	ds_read_b32 v88, v30 offset:2080
	ds_read_b32 v89, v30 offset:2340
	ds_read_b32 v90, v30 offset:2600
	ds_read_b32 v91, v30 offset:2860
	ds_read_b32 v92, v30 offset:3120
	ds_read_b32 v93, v30 offset:3380
	ds_read_b32 v94, v30 offset:3640
	ds_read_b32 v95, v30 offset:3900
	s_waitcnt lgkmcnt(0)
	v_add_f32_e32 v80, v20, v80
	v_add_f32_e32 v81, v20, v81
	v_add_f32_e32 v82, v20, v82
	v_add_f32_e32 v83, v20, v83
	v_add_f32_e32 v84, v20, v84
	v_add_f32_e32 v85, v20, v85
	v_add_f32_e32 v86, v20, v86
	v_add_f32_e32 v87, v20, v87
	v_add_f32_e32 v88, v20, v88
	v_add_f32_e32 v89, v20, v89
	v_add_f32_e32 v90, v20, v90
	v_add_f32_e32 v91, v20, v91
	v_add_f32_e32 v92, v20, v92
	v_add_f32_e32 v93, v20, v93
	v_add_f32_e32 v94, v20, v94
	v_add_f32_e32 v95, v20, v95
	ds_write_b32 v30, v80
	ds_write_b32 v30, v81 offset:260
	ds_write_b32 v30, v82 offset:520
	ds_write_b32 v30, v83 offset:780
	ds_write_b32 v30, v84 offset:1040
	ds_write_b32 v30, v85 offset:1300
	ds_write_b32 v30, v86 offset:1560
	ds_write_b32 v30, v87 offset:1820
	ds_write_b32 v30, v88 offset:2080
	ds_write_b32 v30, v89 offset:2340
	ds_write_b32 v30, v90 offset:2600
	ds_write_b32 v30, v91 offset:2860
	ds_write_b32 v30, v92 offset:3120
	ds_write_b32 v30, v93 offset:3380
	ds_write_b32 v30, v94 offset:3640
	ds_write_b32 v30, v95 offset:3900
	v_and_b32_e32 v9, 63, v22
	v_lshlrev_b32_e32 v10, 2, v9
	v_add_u32_e32 v8, v28, v10
	s_waitcnt lgkmcnt(0)
	s_barrier
	ds_read_b32 v8, v8 offset:16380
	s_movk_i32 s2, 0x90
	v_mad_u32_u24 v9, v9, s2, v28
	v_lshlrev_b32_e32 v11, 5, v17
	s_mov_b32 s2, 0xac00
	v_add3_u32 v9, v9, v11, s2
	v_mul_u32_u24_e32 v11, 0x1040, v17
	v_add3_u32 v10, v28, v11, v10
	v_add_u32_e32 v72, 0x410, v10
	v_add_u32_e32 v73, 0x820, v10
	v_add_u32_e32 v74, 0xc30, v10
	v_add_u32_e32 v76, 0x4400, v10
	v_add_u32_e32 v77, 0x4810, v10
	v_add_u32_e32 v78, 0x4c20, v10
	v_add_u32_e32 v79, 0x5030, v10
	ds_read2_b32 v[96:97], v76 offset1:65
	ds_read2_b32 v[98:99], v10 offset1:65
	ds_read2_b32 v[100:101], v76 offset0:130 offset1:195
	ds_read2_b32 v[102:103], v10 offset0:130 offset1:195
	ds_read2_b32 v[104:105], v77 offset1:65
	ds_read2_b32 v[106:107], v72 offset1:65
	ds_read2_b32 v[108:109], v77 offset0:130 offset1:195
	ds_read2_b32 v[110:111], v72 offset0:130 offset1:195
	ds_read2_b32 v[112:113], v78 offset1:65
	ds_read2_b32 v[114:115], v73 offset1:65
	ds_read2_b32 v[116:117], v78 offset0:130 offset1:195
	ds_read2_b32 v[118:119], v73 offset0:130 offset1:195
	ds_read2_b32 v[120:121], v79 offset1:65
	ds_read2_b32 v[122:123], v74 offset1:65
	ds_read2_b32 v[124:125], v79 offset0:130 offset1:195
	ds_read2_b32 v[126:127], v74 offset0:130 offset1:195
	s_waitcnt lgkmcnt(0)
	v_sub_f32_e32 v98, v8, v98
	v_sub_f32_e32 v99, v8, v99
	v_sub_f32_e32 v102, v8, v102
	v_sub_f32_e32 v103, v8, v103
	v_mul_f32_e32 v98, 0x3fb8aa3b, v98
	v_mul_f32_e32 v99, 0x3fb8aa3b, v99
	v_mul_f32_e32 v102, 0x3fb8aa3b, v102
	v_mul_f32_e32 v103, 0x3fb8aa3b, v103
	v_exp_f32_e32 v98, v98
	v_exp_f32_e32 v99, v99
	v_exp_f32_e32 v102, v102
	v_exp_f32_e32 v103, v103
	s_nop 0
	v_mul_f32_e32 v98, v96, v98
	v_mul_f32_e32 v99, v97, v99
	v_mul_f32_e32 v102, v100, v102
	v_mul_f32_e32 v103, v101, v103
	v_cvt_pk_bf16_f32 v96, v98, v99
	v_cvt_pk_bf16_f32 v97, v102, v103
	ds_write_b64 v9, v[96:97]
	v_sub_f32_e32 v106, v8, v106
	v_sub_f32_e32 v107, v8, v107
	v_sub_f32_e32 v110, v8, v110
	v_sub_f32_e32 v111, v8, v111
	v_mul_f32_e32 v106, 0x3fb8aa3b, v106
	v_mul_f32_e32 v107, 0x3fb8aa3b, v107
	v_mul_f32_e32 v110, 0x3fb8aa3b, v110
	v_mul_f32_e32 v111, 0x3fb8aa3b, v111
	v_exp_f32_e32 v106, v106
	v_exp_f32_e32 v107, v107
	v_exp_f32_e32 v110, v110
	v_exp_f32_e32 v111, v111
	s_nop 0
	v_mul_f32_e32 v106, v104, v106
	v_mul_f32_e32 v107, v105, v107
	v_mul_f32_e32 v110, v108, v110
	v_mul_f32_e32 v111, v109, v111
	v_cvt_pk_bf16_f32 v104, v106, v107
	v_cvt_pk_bf16_f32 v105, v110, v111
	ds_write_b64 v9, v[104:105] offset:8
	v_sub_f32_e32 v114, v8, v114
	v_sub_f32_e32 v115, v8, v115
	v_sub_f32_e32 v118, v8, v118
	v_sub_f32_e32 v119, v8, v119
	v_mul_f32_e32 v114, 0x3fb8aa3b, v114
	v_mul_f32_e32 v115, 0x3fb8aa3b, v115
	v_mul_f32_e32 v118, 0x3fb8aa3b, v118
	v_mul_f32_e32 v119, 0x3fb8aa3b, v119
	v_exp_f32_e32 v114, v114
	v_exp_f32_e32 v115, v115
	v_exp_f32_e32 v118, v118
	v_exp_f32_e32 v119, v119
	s_nop 0
	v_mul_f32_e32 v114, v112, v114
	v_mul_f32_e32 v115, v113, v115
	v_mul_f32_e32 v118, v116, v118
	v_mul_f32_e32 v119, v117, v119
	v_cvt_pk_bf16_f32 v112, v114, v115
	v_cvt_pk_bf16_f32 v113, v118, v119
	ds_write_b64 v9, v[112:113] offset:16
	v_sub_f32_e32 v122, v8, v122
	v_sub_f32_e32 v123, v8, v123
	v_sub_f32_e32 v126, v8, v126
	v_sub_f32_e32 v127, v8, v127
	v_mul_f32_e32 v122, 0x3fb8aa3b, v122
	v_mul_f32_e32 v123, 0x3fb8aa3b, v123
	v_mul_f32_e32 v126, 0x3fb8aa3b, v126
	v_mul_f32_e32 v127, 0x3fb8aa3b, v127
	v_exp_f32_e32 v122, v122
	v_exp_f32_e32 v123, v123
	v_exp_f32_e32 v126, v126
	v_exp_f32_e32 v127, v127
	s_nop 0
	v_mul_f32_e32 v122, v120, v122
	v_mul_f32_e32 v123, v121, v123
	v_mul_f32_e32 v126, v124, v126
	v_mul_f32_e32 v127, v125, v127
	v_cvt_pk_bf16_f32 v120, v122, v123
	v_cvt_pk_bf16_f32 v121, v126, v127
	ds_write_b64 v9, v[120:121] offset:24
	v_lshl_add_u32 v12, v29, 1, v28
	s_movk_i32 s2, 0x90
	v_mad_u32_u24 v17, v19, s2, v12
	s_waitcnt lgkmcnt(0)
	s_barrier
	ds_read_b128 v[8:11], v17 offset:34816
	v_mad_u32_u24 v18, v26, s2, v12
	ds_read_b128 v[80:83], v18 offset:44032
	ds_read_b128 v[84:87], v18 offset:46336
	ds_read_b128 v[88:91], v18 offset:48640
	ds_read_b128 v[92:95], v18 offset:50944
	ds_read_b128 v[96:99], v17 offset:34880
	ds_read_b128 v[100:103], v18 offset:44096
	ds_read_b128 v[104:107], v18 offset:46400
	ds_read_b128 v[108:111], v18 offset:48704
	ds_read_b128 v[112:115], v18 offset:51008
	s_waitcnt lgkmcnt(3)
	v_mfma_f32_16x16x32_bf16 v[12:15], v[80:83], v[8:11], 0
	v_lshlrev_b32_e32 v30, 2, v23
	v_mov_b32_e32 v33, v177
	v_or_b32_e32 v51, 16, v26
	s_waitcnt lgkmcnt(2)
	v_mfma_f32_16x16x32_bf16 v[34:37], v[84:87], v[8:11], 0
	v_or_b32_e32 v48, 32, v26
	v_or_b32_e32 v31, 48, v26
	v_cmp_lt_u32_sdwa s[4:5], v22, v216 src0_sel:BYTE_0 src1_sel:DWORD
	s_waitcnt lgkmcnt(1)
	v_mfma_f32_16x16x32_bf16 v[38:41], v[88:91], v[8:11], 0
	s_waitcnt lgkmcnt(0)
	v_mfma_f32_16x16x32_bf16 v[8:11], v[92:95], v[8:11], 0
	v_ashrrev_i32_e32 v17, 31, v16
	v_lshlrev_b64 v[20:21], 14, v[16:17]
	s_waitcnt lgkmcnt(0)
	v_mfma_f32_16x16x32_bf16 v[12:15], v[100:103], v[96:99], v[12:15]
	v_lshl_add_u64 v[20:21], s[78:79], 0, v[20:21]
	s_waitcnt lgkmcnt(0)
	v_mfma_f32_16x16x32_bf16 v[34:37], v[104:107], v[96:99], v[34:37]
	s_waitcnt lgkmcnt(0)
	v_mfma_f32_16x16x32_bf16 v[38:41], v[108:111], v[96:99], v[38:41]
	v_or_b32_e32 v66, v32, v26
	v_lshl_or_b32 v66, v66, 6, v30
	v_lshlrev_b32_e32 v66, 2, v66
	v_mov_b32_e32 v67, v177
	v_lshl_add_u64 v[66:67], v[20:21], 0, v[66:67]
	v_or_b32_e32 v18, v32, v30
	v_lshlrev_b32_e32 v18, 6, v18
	v_or_b32_e32 v23, v18, v26
	v_lshlrev_b32_e32 v32, 2, v23
	v_lshl_add_u64 v[32:33], v[20:21], 0, v[32:33]
	global_store_dwordx4 v[66:67], v[12:15], off sc1
	global_store_dwordx4 v[66:67], v[34:37], off offset:64 sc1
	global_store_dwordx4 v[66:67], v[38:41], off offset:128 sc1
	s_nop 1
	v_or_b32_e32 v12, v18, v51
	v_lshlrev_b32_e32 v12, 2, v12
	v_mov_b32_e32 v13, v177
	v_lshl_add_u64 v[12:13], v[20:21], 0, v[12:13]
	v_or_b32_e32 v12, v18, v48
	v_lshlrev_b32_e32 v12, 2, v12
	v_mov_b32_e32 v13, v177
	s_waitcnt lgkmcnt(0)
	v_mfma_f32_16x16x32_bf16 v[8:11], v[112:115], v[96:99], v[8:11]
	v_lshl_add_u64 v[12:13], v[20:21], 0, v[12:13]
	s_nop 3
	s_nop 3
	global_store_dwordx4 v[66:67], v[8:11], off offset:192 sc1
	s_nop 1
	v_or_b32_e32 v8, v18, v31
	v_lshlrev_b32_e32 v12, 2, v8
	v_mov_b32_e32 v13, v177
	v_lshl_add_u64 v[12:13], v[20:21], 0, v[12:13]
	s_waitcnt lgkmcnt(0)
	v_mov_b32_e32 v42, v96
	v_mov_b32_e32 v43, v97
	v_mov_b32_e32 v44, v98
	v_mov_b32_e32 v45, v99
	v_mov_b32_e32 v52, v112
	v_mov_b32_e32 v53, v113
	v_mov_b32_e32 v54, v114
	v_mov_b32_e32 v55, v115
	s_and_saveexec_b64 s[2:3], s[4:5]
	s_cbranch_execz .LBB0_244
	v_lshlrev_b32_sdwa v8, v213, v22 dst_sel:DWORD dst_unused:UNUSED_PAD src0_sel:DWORD src1_sel:BYTE_0
	v_add_u32_e32 v9, v28, v8
	ds_read_b32 v9, v9 offset:16380
	v_readlane_b32 s4, v254, 21
	v_lshlrev_b64 v[10:11], 8, v[16:17]
	v_readlane_b32 s5, v254, 22
	s_waitcnt lgkmcnt(0)
	v_mul_f32_e32 v9, 0x3fb8aa3b, v9
	v_exp_f32_e32 v12, v9
	v_lshl_add_u64 v[10:11], s[4:5], 0, v[10:11]
	v_mov_b32_e32 v9, v177
	v_lshl_add_u64 v[8:9], v[10:11], 0, v[8:9]
	global_store_dword v[8:9], v12, off
.LBB0_244:
	s_or_b64 exec, exec, s[2:3]
	s_movk_i32 s2, 0x1040
	v_mad_u32_u24 v23, v27, s2, v28
	v_add_u32_e32 v8, 0xfffffefc, v23
	v_cmp_eq_u32_e64 s[36:37], 0, v27
	v_cmp_ne_u32_e32 vcc, 0, v27
	v_mov_b32_e32 v32, 0
	v_lshl_add_u32 v50, v29, 2, v8
	v_mov_b32_e32 v33, 0
	s_and_saveexec_b64 s[2:3], vcc
	ds_read_b32 v33, v50
	s_or_b64 exec, exec, s[2:3]
	v_lshlrev_b32_e32 v49, 2, v29
	s_and_saveexec_b64 s[2:3], vcc
	s_movk_i32 s4, 0xff00
	v_add3_u32 v8, v23, v49, s4
	ds_read_b32 v32, v8
	s_or_b64 exec, exec, s[2:3]
	v_mul_u32_u24_e32 v8, 0x104, v19
	v_add3_u32 v22, v28, v8, v49
	ds_read2_b32 v[8:9], v22 offset1:1
	v_mov_b32_e32 v36, 0
	v_mov_b32_e32 v38, 0
	s_and_saveexec_b64 s[2:3], vcc
	ds_read_b32 v38, v50 offset:8
	s_or_b64 exec, exec, s[2:3]
	s_and_saveexec_b64 s[2:3], vcc
	s_movk_i32 s4, 0xff08
	v_add3_u32 v10, v23, v49, s4
	ds_read_b32 v36, v10
	s_or_b64 exec, exec, s[2:3]
	ds_read2_b32 v[10:11], v22 offset0:2 offset1:3
	v_mov_b32_e32 v39, 0
	v_mov_b32_e32 v42, 0
	s_and_saveexec_b64 s[2:3], vcc
	ds_read_b32 v42, v50 offset:16
	s_or_b64 exec, exec, s[2:3]
	s_and_saveexec_b64 s[2:3], vcc
	s_movk_i32 s4, 0xff10
	v_add3_u32 v12, v23, v49, s4
	ds_read_b32 v39, v12
	s_or_b64 exec, exec, s[2:3]
	ds_read2_b32 v[12:13], v22 offset0:4 offset1:5
	v_mov_b32_e32 v44, 0
	v_mov_b32_e32 v46, 0
	s_and_saveexec_b64 s[2:3], vcc
	ds_read_b32 v46, v50 offset:24
	s_or_b64 exec, exec, s[2:3]
	s_and_saveexec_b64 s[2:3], vcc
	s_movk_i32 s4, 0xff18
	v_add3_u32 v14, v23, v49, s4
	ds_read_b32 v44, v14
	s_or_b64 exec, exec, s[2:3]
	ds_read2_b32 v[14:15], v22 offset0:6 offset1:7
	v_mov_b32_e32 v34, 0
	v_mov_b32_e32 v35, 0
	s_and_saveexec_b64 s[2:3], vcc
	ds_read_b32 v35, v50 offset:128
	s_or_b64 exec, exec, s[2:3]
	s_and_saveexec_b64 s[2:3], vcc
	s_movk_i32 s4, 0xff80
	v_add3_u32 v16, v23, v49, s4
	ds_read_b32 v34, v16
	s_or_b64 exec, exec, s[2:3]
	ds_read2_b32 v[16:17], v22 offset0:32 offset1:33
	v_mov_b32_e32 v37, 0
	v_mov_b32_e32 v40, 0
	s_and_saveexec_b64 s[2:3], vcc
	ds_read_b32 v40, v50 offset:136
	s_or_b64 exec, exec, s[2:3]
	s_and_saveexec_b64 s[2:3], vcc
	s_movk_i32 s4, 0xff88
	v_add3_u32 v18, v23, v49, s4
	ds_read_b32 v37, v18
	s_or_b64 exec, exec, s[2:3]
	ds_read2_b32 v[18:19], v22 offset0:34 offset1:35
	v_mov_b32_e32 v41, 0
	v_mov_b32_e32 v43, 0
	s_and_saveexec_b64 s[2:3], vcc
	ds_read_b32 v43, v50 offset:144
	s_or_b64 exec, exec, s[2:3]
	s_and_saveexec_b64 s[2:3], vcc
	s_movk_i32 s4, 0xff90
	v_add3_u32 v20, v23, v49, s4
	ds_read_b32 v41, v20
	s_or_b64 exec, exec, s[2:3]
	ds_read2_b32 v[20:21], v22 offset0:36 offset1:37
	v_mov_b32_e32 v45, 0
	v_mov_b32_e32 v47, 0
	s_and_saveexec_b64 s[2:3], vcc
	ds_read_b32 v47, v50 offset:152
	s_or_b64 exec, exec, s[2:3]
	s_and_saveexec_b64 s[2:3], vcc
	s_movk_i32 s4, 0xff98
	v_add3_u32 v23, v23, v49, s4
	ds_read_b32 v45, v23
	s_or_b64 exec, exec, s[2:3]
	s_waitcnt lgkmcnt(2)
	v_sub_f32_e32 v23, v16, v35
	v_mul_f32_e32 v23, 0x3fb8aa3b, v23
	v_exp_f32_e32 v52, v23
	v_sub_f32_e32 v23, v17, v34
	v_mul_f32_e32 v16, 0x3fb8aa3b, v16
	v_mul_f32_e32 v17, 0x3fb8aa3b, v17
	v_exp_f32_e32 v16, v16
	v_exp_f32_e32 v17, v17
	v_mul_f32_e32 v23, 0x3fb8aa3b, v23
	v_exp_f32_e32 v53, v23
	v_lshlrev_b32_e32 v54, 16, v0
	v_and_b32_e32 v55, 0xffff0000, v0
	v_pk_mul_f32 v[16:17], v[16:17], v[54:55]
	v_pk_mul_f32 v[52:53], v[52:53], v[54:55]
	v_cvt_pk_bf16_f32 v16, v16, v17
	s_waitcnt lgkmcnt(1)
	v_sub_f32_e32 v17, v18, v40
	v_mul_f32_e32 v17, 0x3fb8aa3b, v17
	v_cvt_pk_bf16_f32 v0, v52, v53
	v_exp_f32_e32 v52, v17
	v_sub_f32_e32 v17, v19, v37
	v_mul_f32_e32 v17, 0x3fb8aa3b, v17
	v_exp_f32_e32 v53, v17
	v_mul_f32_e32 v17, 0x3fb8aa3b, v18
	v_exp_f32_e32 v18, v17
	v_mul_f32_e32 v17, 0x3fb8aa3b, v19
	v_exp_f32_e32 v19, v17
	v_lshlrev_b32_e32 v54, 16, v1
	v_and_b32_e32 v55, 0xffff0000, v1
	v_pk_mul_f32 v[52:53], v[52:53], v[54:55]
	v_pk_mul_f32 v[18:19], v[18:19], v[54:55]
	v_cvt_pk_bf16_f32 v1, v52, v53
	v_cvt_pk_bf16_f32 v17, v18, v19
	s_waitcnt lgkmcnt(0)
	v_sub_f32_e32 v18, v20, v43
	v_sub_f32_e32 v19, v21, v41
	v_mul_f32_e32 v18, 0x3fb8aa3b, v18
	v_mul_f32_e32 v19, 0x3fb8aa3b, v19
	v_exp_f32_e32 v18, v18
	v_exp_f32_e32 v19, v19
	v_mul_f32_e32 v20, 0x3fb8aa3b, v20
	v_mul_f32_e32 v21, 0x3fb8aa3b, v21
	v_exp_f32_e32 v20, v20
	v_exp_f32_e32 v21, v21
	v_lshlrev_b32_e32 v52, 16, v2
	v_and_b32_e32 v53, 0xffff0000, v2
	v_pk_mul_f32 v[18:19], v[18:19], v[52:53]
	s_movk_i32 s4, 0x300
	v_cvt_pk_bf16_f32 v2, v18, v19
	v_pk_mul_f32 v[18:19], v[20:21], v[52:53]
	v_lshlrev_b32_e32 v52, 16, v4
	v_cvt_pk_bf16_f32 v18, v18, v19
	v_sub_f32_e32 v19, v8, v33
	v_mul_f32_e32 v19, 0x3fb8aa3b, v19
	v_exp_f32_e32 v20, v19
	v_sub_f32_e32 v19, v9, v32
	v_mul_f32_e32 v8, 0x3fb8aa3b, v8
	v_mul_f32_e32 v9, 0x3fb8aa3b, v9
	v_exp_f32_e32 v8, v8
	v_exp_f32_e32 v9, v9
	v_mul_f32_e32 v19, 0x3fb8aa3b, v19
	v_exp_f32_e32 v21, v19
	v_and_b32_e32 v53, 0xffff0000, v4
	v_pk_mul_f32 v[8:9], v[8:9], v[52:53]
	v_or_b32_e32 v50, 2, v30
	v_cvt_pk_bf16_f32 v8, v8, v9
	v_sub_f32_e32 v9, v10, v38
	v_pk_mul_f32 v[20:21], v[20:21], v[52:53]
	v_mul_f32_e32 v9, 0x3fb8aa3b, v9
	v_cvt_pk_bf16_f32 v4, v20, v21
	v_exp_f32_e32 v20, v9
	v_sub_f32_e32 v9, v11, v36
	v_mul_f32_e32 v9, 0x3fb8aa3b, v9
	v_exp_f32_e32 v21, v9
	v_mul_f32_e32 v9, 0x3fb8aa3b, v10
	v_exp_f32_e32 v10, v9
	v_mul_f32_e32 v9, 0x3fb8aa3b, v11
	v_exp_f32_e32 v11, v9
	v_lshlrev_b32_e32 v52, 16, v5
	v_and_b32_e32 v53, 0xffff0000, v5
	v_pk_mul_f32 v[20:21], v[20:21], v[52:53]
	v_pk_mul_f32 v[10:11], v[10:11], v[52:53]
	v_cvt_pk_bf16_f32 v5, v20, v21
	v_cvt_pk_bf16_f32 v9, v10, v11
	v_sub_f32_e32 v10, v12, v42
	v_sub_f32_e32 v11, v13, v39
	v_mul_f32_e32 v10, 0x3fb8aa3b, v10
	v_mul_f32_e32 v11, 0x3fb8aa3b, v11
	v_exp_f32_e32 v10, v10
	v_exp_f32_e32 v11, v11
	v_mul_f32_e32 v12, 0x3fb8aa3b, v12
	v_mul_f32_e32 v13, 0x3fb8aa3b, v13
	v_exp_f32_e32 v12, v12
	v_exp_f32_e32 v13, v13
	v_lshlrev_b32_e32 v20, 16, v6
	v_and_b32_e32 v21, 0xffff0000, v6
	v_pk_mul_f32 v[10:11], v[10:11], v[20:21]
	v_or_b32_e32 v49, 3, v30
	v_cvt_pk_bf16_f32 v6, v10, v11
	v_pk_mul_f32 v[10:11], v[12:13], v[20:21]
	v_lshlrev_b32_e32 v20, 16, v7
	v_cvt_pk_bf16_f32 v10, v10, v11
	v_sub_f32_e32 v11, v14, v46
	v_mul_f32_e32 v11, 0x3fb8aa3b, v11
	v_exp_f32_e32 v12, v11
	v_sub_f32_e32 v11, v15, v44
	v_mul_f32_e32 v11, 0x3fb8aa3b, v11
	v_exp_f32_e32 v13, v11
	v_mul_f32_e32 v11, 0x3fb8aa3b, v14
	v_exp_f32_e32 v14, v11
	v_mul_f32_e32 v11, 0x3fb8aa3b, v15
	v_exp_f32_e32 v15, v11
	v_and_b32_e32 v21, 0xffff0000, v7
	v_pk_mul_f32 v[12:13], v[12:13], v[20:21]
	s_nop 0
	v_cvt_pk_bf16_f32 v7, v12, v13
	v_pk_mul_f32 v[12:13], v[14:15], v[20:21]
	v_lshlrev_b32_e32 v20, 16, v3
	v_cvt_pk_bf16_f32 v11, v12, v13
	ds_read2_b32 v[12:13], v22 offset0:38 offset1:39
	v_and_b32_e32 v21, 0xffff0000, v3
	s_waitcnt lgkmcnt(0)
	v_sub_f32_e32 v14, v12, v47
	v_sub_f32_e32 v15, v13, v45
	v_mul_f32_e32 v12, 0x3fb8aa3b, v12
	v_mul_f32_e32 v13, 0x3fb8aa3b, v13
	v_exp_f32_e32 v12, v12
	v_exp_f32_e32 v13, v13
	v_mul_f32_e32 v14, 0x3fb8aa3b, v14
	v_mul_f32_e32 v15, 0x3fb8aa3b, v15
	v_exp_f32_e32 v14, v14
	v_exp_f32_e32 v15, v15
	v_pk_mul_f32 v[12:13], v[12:13], v[20:21]
	v_pk_mul_f32 v[14:15], v[14:15], v[20:21]
	v_cvt_pk_bf16_f32 v19, v12, v13
	v_mov_b64_e32 v[12:13], s[64:65]
	v_mad_u64_u32 v[12:13], s[2:3], v24, s4, v[12:13]
	v_cvt_pk_bf16_f32 v3, v14, v15
	v_mov_b32_e32 v14, v13
	v_mad_u64_u32 v[14:15], s[2:3], v25, s4, v[14:15]
	v_mov_b32_e32 v13, v14
	v_lshl_add_u64 v[12:13], v[12:13], 0, v[176:177]
	v_lshlrev_b32_e32 v14, 1, v29
	v_mov_b32_e32 v15, v177
	v_lshl_add_u64 v[12:13], v[12:13], 0, v[14:15]
	s_movk_i32 s2, 0x41
	global_store_dwordx4 v[12:13], v[8:11], off sc1
	global_store_dwordx4 v[12:13], v[16:19], off offset:64 sc1
	s_nop 0
	v_mad_u32_u24 v8, v26, s2, v29
	v_lshl_add_u32 v15, v8, 2, v28
	ds_read2_b32 v[80:81], v15 offset1:1
	v_add_u32_e32 v84, 0x4400, v15
	ds_read2_b32 v[82:83], v84 offset1:1
	ds_read2_b32 v[86:87], v15 offset0:2 offset1:3
	v_add_u32_e32 v85, 0x4408, v15
	ds_read2_b32 v[88:89], v85 offset1:1
	ds_read2_b32 v[90:91], v15 offset0:4 offset1:5
	v_add_u32_e32 v94, 0x4410, v15
	ds_read2_b32 v[92:93], v94 offset1:1
	ds_read2_b32 v[96:97], v15 offset0:6 offset1:7
	v_add_u32_e32 v95, 0x4418, v15
	ds_read2_b32 v[98:99], v95 offset1:1
	ds_read2_b32 v[100:101], v15 offset0:32 offset1:33
	v_add_u32_e32 v104, 0x4480, v15
	ds_read2_b32 v[102:103], v104 offset1:1
	ds_read2_b32 v[106:107], v15 offset0:34 offset1:35
	v_add_u32_e32 v105, 0x4488, v15
	ds_read2_b32 v[108:109], v105 offset1:1
	ds_read2_b32 v[110:111], v15 offset0:36 offset1:37
	v_add_u32_e32 v114, 0x4490, v15
	ds_read2_b32 v[112:113], v114 offset1:1
	ds_read2_b32 v[116:117], v15 offset0:38 offset1:39
	v_add_u32_e32 v115, 0x4498, v15
	ds_read2_b32 v[118:119], v115 offset1:1
	v_add_u32_e32 v10, 0x4400, v15
	v_add_u32_e32 v14, 0x4480, v15
	s_waitcnt lgkmcnt(1)
	v_sub_f32_e32 v8, v33, v80
	v_sub_f32_e32 v9, v32, v81
	v_min_f32_e32 v8, 0x42a00000, v8
	v_min_f32_e32 v9, 0x42a00000, v9
	v_mul_f32_e32 v8, 0x3fb8aa3b, v8
	v_mul_f32_e32 v9, 0x3fb8aa3b, v9
	v_exp_f32_e32 v8, v8
	v_exp_f32_e32 v9, v9
	s_waitcnt lgkmcnt(0)
	v_pk_mul_f32 v[8:9], v[82:83], v[8:9]
	v_cvt_pk_bf16_f32 v8, v8, v9
	v_add_u32_e32 v9, 0x4408, v15
	s_waitcnt lgkmcnt(1)
	v_sub_f32_e32 v10, v38, v86
	v_sub_f32_e32 v11, v36, v87
	v_min_f32_e32 v10, 0x42a00000, v10
	v_min_f32_e32 v11, 0x42a00000, v11
	v_mul_f32_e32 v10, 0x3fb8aa3b, v10
	v_mul_f32_e32 v11, 0x3fb8aa3b, v11
	v_exp_f32_e32 v10, v10
	v_exp_f32_e32 v11, v11
	s_waitcnt lgkmcnt(0)
	v_pk_mul_f32 v[10:11], v[88:89], v[10:11]
	s_nop 0
	v_cvt_pk_bf16_f32 v9, v10, v11
	v_add_u32_e32 v12, 0x4410, v15
	s_waitcnt lgkmcnt(1)
	v_sub_f32_e32 v10, v42, v90
	v_sub_f32_e32 v11, v39, v91
	v_min_f32_e32 v10, 0x42a00000, v10
	v_min_f32_e32 v11, 0x42a00000, v11
	v_mul_f32_e32 v10, 0x3fb8aa3b, v10
	v_mul_f32_e32 v11, 0x3fb8aa3b, v11
	v_exp_f32_e32 v10, v10
	v_exp_f32_e32 v11, v11
	s_waitcnt lgkmcnt(0)
	v_pk_mul_f32 v[10:11], v[92:93], v[10:11]
	v_cvt_pk_bf16_f32 v10, v10, v11
	v_add_u32_e32 v11, 0x4418, v15
	s_waitcnt lgkmcnt(1)
	v_sub_f32_e32 v12, v46, v96
	v_sub_f32_e32 v13, v44, v97
	v_min_f32_e32 v12, 0x42a00000, v12
	v_min_f32_e32 v13, 0x42a00000, v13
	v_mul_f32_e32 v12, 0x3fb8aa3b, v12
	v_mul_f32_e32 v13, 0x3fb8aa3b, v13
	v_exp_f32_e32 v12, v12
	v_exp_f32_e32 v13, v13
	s_waitcnt lgkmcnt(0)
	v_pk_mul_f32 v[12:13], v[98:99], v[12:13]
	s_nop 0
	v_cvt_pk_bf16_f32 v11, v12, v13
	s_nop 1
	v_mfma_f32_16x16x32_bf16 v[8:11], v[8:11], v[4:7], 0
	s_waitcnt lgkmcnt(1)
	v_sub_f32_e32 v12, v35, v100
	v_sub_f32_e32 v13, v34, v101
	v_min_f32_e32 v12, 0x42a00000, v12
	v_min_f32_e32 v13, 0x42a00000, v13
	v_mul_f32_e32 v12, 0x3fb8aa3b, v12
	v_mul_f32_e32 v13, 0x3fb8aa3b, v13
	v_exp_f32_e32 v12, v12
	v_exp_f32_e32 v13, v13
	s_waitcnt lgkmcnt(0)
	v_pk_mul_f32 v[12:13], v[102:103], v[12:13]
	v_cvt_pk_bf16_f32 v12, v12, v13
	v_add_u32_e32 v13, 0x4488, v15
	s_waitcnt lgkmcnt(1)
	v_sub_f32_e32 v14, v40, v106
	v_min_f32_e32 v14, 0x42a00000, v14
	v_mul_f32_e32 v14, 0x3fb8aa3b, v14
	v_exp_f32_e32 v16, v14
	v_sub_f32_e32 v14, v37, v107
	v_min_f32_e32 v14, 0x42a00000, v14
	v_mul_f32_e32 v14, 0x3fb8aa3b, v14
	v_exp_f32_e32 v17, v14
	v_add_u32_e32 v14, 0x4490, v15
	s_waitcnt lgkmcnt(0)
	v_pk_mul_f32 v[16:17], v[108:109], v[16:17]
	s_nop 0
	v_cvt_pk_bf16_f32 v13, v16, v17
	s_waitcnt lgkmcnt(1)
	v_sub_f32_e32 v16, v43, v110
	v_sub_f32_e32 v17, v41, v111
	v_min_f32_e32 v16, 0x42a00000, v16
	v_min_f32_e32 v17, 0x42a00000, v17
	v_mul_f32_e32 v16, 0x3fb8aa3b, v16
	v_mul_f32_e32 v17, 0x3fb8aa3b, v17
	v_exp_f32_e32 v16, v16
	v_exp_f32_e32 v17, v17
	s_waitcnt lgkmcnt(0)
	v_pk_mul_f32 v[16:17], v[112:113], v[16:17]
	s_nop 0
	v_cvt_pk_bf16_f32 v14, v16, v17
	v_add_u32_e32 v18, 0x4498, v15
	s_waitcnt lgkmcnt(1)
	v_sub_f32_e32 v15, v47, v116
	v_min_f32_e32 v15, 0x42a00000, v15
	v_mul_f32_e32 v15, 0x3fb8aa3b, v15
	v_exp_f32_e32 v16, v15
	v_sub_f32_e32 v15, v45, v117
	v_min_f32_e32 v15, 0x42a00000, v15
	v_mul_f32_e32 v15, 0x3fb8aa3b, v15
	v_exp_f32_e32 v17, v15
	s_waitcnt lgkmcnt(0)
	v_pk_mul_f32 v[16:17], v[118:119], v[16:17]
	s_nop 0
	v_cvt_pk_bf16_f32 v15, v16, v17
	v_mov_b32_e32 v16, 0
	s_nop 0
	v_mfma_f32_16x16x32_bf16 v[8:11], v[12:15], v[0:3], v[8:11]
	s_waitcnt lgkmcnt(0)
	v_mov_b32_e32 v18, v118
	v_mov_b32_e32 v19, v119
	s_and_saveexec_b64 s[2:3], s[36:37]
	v_cmp_gt_u32_e64 s[36:37], v30, v26
	s_nop 5
	v_cndmask_b32_e64 v12, v8, 0, s[36:37]
	v_cmp_lt_u32_e64 s[36:37], v30, v26
	s_nop 1
	v_cndmask_b32_e64 v8, v12, v8, s[36:37]
	v_cndmask_b32_e64 v9, 0, v9, s[36:37]
	v_cmp_le_u32_e64 s[36:37], v50, v26
	s_nop 1
	v_cndmask_b32_e64 v10, 0, v10, s[36:37]
	v_cmp_le_u32_e64 s[36:37], v49, v26
	s_nop 1
	v_cndmask_b32_e64 v11, 0, v11, s[36:37]
	s_or_b64 exec, exec, s[2:3]
	v_mov_b32_e32 v20, 0
	v_mov_b32_e32 v21, 0
	v_mov_b32_e32 v22, 0
	v_mov_b32_e32 v23, 0
	s_and_saveexec_b64 s[4:5], vcc
	s_cbranch_execz .LBB0_282
	s_movk_i32 s2, 0x41
	v_mad_u32_u24 v12, v51, s2, v29
	v_lshl_add_u32 v17, v12, 2, v28
	ds_read2_b32 v[80:81], v17 offset1:1
	v_add_u32_e32 v84, 0x4400, v17
	ds_read2_b32 v[82:83], v84 offset1:1
	ds_read2_b32 v[86:87], v17 offset0:2 offset1:3
	v_add_u32_e32 v85, 0x4408, v17
	ds_read2_b32 v[88:89], v85 offset1:1
	ds_read2_b32 v[90:91], v17 offset0:4 offset1:5
	v_add_u32_e32 v94, 0x4410, v17
	ds_read2_b32 v[92:93], v94 offset1:1
	ds_read2_b32 v[96:97], v17 offset0:6 offset1:7
	v_add_u32_e32 v95, 0x4418, v17
	ds_read2_b32 v[98:99], v95 offset1:1
	ds_read2_b32 v[100:101], v17 offset0:32 offset1:33
	v_add_u32_e32 v104, 0x4480, v17
	ds_read2_b32 v[102:103], v104 offset1:1
	ds_read2_b32 v[106:107], v17 offset0:34 offset1:35
	v_add_u32_e32 v105, 0x4488, v17
	ds_read2_b32 v[108:109], v105 offset1:1
	ds_read2_b32 v[110:111], v17 offset0:36 offset1:37
	v_add_u32_e32 v114, 0x4490, v17
	ds_read2_b32 v[112:113], v114 offset1:1
	ds_read2_b32 v[116:117], v17 offset0:38 offset1:39
	v_add_u32_e32 v115, 0x4498, v17
	ds_read2_b32 v[118:119], v115 offset1:1
	v_add_u32_e32 v14, 0x4400, v17
	v_cmp_eq_u32_e32 vcc, 1, v27
	s_waitcnt lgkmcnt(1)
	v_sub_f32_e32 v12, v33, v80
	v_sub_f32_e32 v13, v32, v81
	v_min_f32_e32 v12, 0x42a00000, v12
	v_min_f32_e32 v13, 0x42a00000, v13
	v_mul_f32_e32 v12, 0x3fb8aa3b, v12
	v_mul_f32_e32 v13, 0x3fb8aa3b, v13
	v_exp_f32_e32 v12, v12
	v_exp_f32_e32 v13, v13
	s_waitcnt lgkmcnt(0)
	v_pk_mul_f32 v[12:13], v[82:83], v[12:13]
	v_cvt_pk_bf16_f32 v12, v12, v13
	v_add_u32_e32 v13, 0x4408, v17
	s_waitcnt lgkmcnt(1)
	v_sub_f32_e32 v14, v38, v86
	v_sub_f32_e32 v15, v36, v87
	v_min_f32_e32 v14, 0x42a00000, v14
	v_min_f32_e32 v15, 0x42a00000, v15
	v_mul_f32_e32 v14, 0x3fb8aa3b, v14
	v_mul_f32_e32 v15, 0x3fb8aa3b, v15
	v_exp_f32_e32 v14, v14
	v_exp_f32_e32 v15, v15
	s_waitcnt lgkmcnt(0)
	v_pk_mul_f32 v[14:15], v[88:89], v[14:15]
	s_nop 0
	v_cvt_pk_bf16_f32 v13, v14, v15
	v_add_u32_e32 v18, 0x4410, v17
	s_waitcnt lgkmcnt(1)
	v_sub_f32_e32 v14, v42, v90
	v_sub_f32_e32 v15, v39, v91
	v_min_f32_e32 v14, 0x42a00000, v14
	v_min_f32_e32 v15, 0x42a00000, v15
	v_mul_f32_e32 v14, 0x3fb8aa3b, v14
	v_mul_f32_e32 v15, 0x3fb8aa3b, v15
	v_exp_f32_e32 v14, v14
	v_exp_f32_e32 v15, v15
	s_waitcnt lgkmcnt(0)
	v_pk_mul_f32 v[14:15], v[92:93], v[14:15]
	v_cvt_pk_bf16_f32 v14, v14, v15
	v_add_u32_e32 v15, 0x4418, v17
	s_waitcnt lgkmcnt(1)
	v_sub_f32_e32 v18, v46, v96
	v_sub_f32_e32 v19, v44, v97
	v_min_f32_e32 v18, 0x42a00000, v18
	v_min_f32_e32 v19, 0x42a00000, v19
	v_mul_f32_e32 v18, 0x3fb8aa3b, v18
	v_mul_f32_e32 v19, 0x3fb8aa3b, v19
	v_exp_f32_e32 v18, v18
	v_exp_f32_e32 v19, v19
	s_waitcnt lgkmcnt(0)
	v_pk_mul_f32 v[18:19], v[98:99], v[18:19]
	s_nop 0
	v_cvt_pk_bf16_f32 v15, v18, v19
	v_add_u32_e32 v20, 0x4480, v17
	s_nop 0
	v_mfma_f32_16x16x32_bf16 v[12:15], v[12:15], v[4:7], 0
	s_waitcnt lgkmcnt(1)
	v_sub_f32_e32 v18, v35, v100
	v_sub_f32_e32 v19, v34, v101
	v_min_f32_e32 v18, 0x42a00000, v18
	v_min_f32_e32 v19, 0x42a00000, v19
	v_mul_f32_e32 v18, 0x3fb8aa3b, v18
	v_mul_f32_e32 v19, 0x3fb8aa3b, v19
	v_exp_f32_e32 v18, v18
	v_exp_f32_e32 v19, v19
	s_waitcnt lgkmcnt(0)
	v_pk_mul_f32 v[18:19], v[102:103], v[18:19]
	v_cvt_pk_bf16_f32 v18, v18, v19
	v_add_u32_e32 v19, 0x4488, v17
	s_waitcnt lgkmcnt(1)
	v_sub_f32_e32 v20, v40, v106
	v_sub_f32_e32 v21, v37, v107
	v_min_f32_e32 v20, 0x42a00000, v20
	v_min_f32_e32 v21, 0x42a00000, v21
	v_mul_f32_e32 v20, 0x3fb8aa3b, v20
	v_mul_f32_e32 v21, 0x3fb8aa3b, v21
	v_exp_f32_e32 v20, v20
	v_exp_f32_e32 v21, v21
	s_waitcnt lgkmcnt(0)
	v_pk_mul_f32 v[20:21], v[108:109], v[20:21]
	s_nop 0
	v_cvt_pk_bf16_f32 v19, v20, v21
	v_add_u32_e32 v22, 0x4490, v17
	s_waitcnt lgkmcnt(1)
	v_sub_f32_e32 v20, v43, v110
	v_sub_f32_e32 v21, v41, v111
	v_min_f32_e32 v20, 0x42a00000, v20
	v_min_f32_e32 v21, 0x42a00000, v21
	v_mul_f32_e32 v20, 0x3fb8aa3b, v20
	v_mul_f32_e32 v21, 0x3fb8aa3b, v21
	v_exp_f32_e32 v20, v20
	v_exp_f32_e32 v21, v21
	s_waitcnt lgkmcnt(0)
	v_pk_mul_f32 v[20:21], v[112:113], v[20:21]
	v_cvt_pk_bf16_f32 v20, v20, v21
	v_add_u32_e32 v21, 0x4498, v17
	s_waitcnt lgkmcnt(1)
	v_sub_f32_e32 v17, v47, v116
	v_min_f32_e32 v17, 0x42a00000, v17
	v_mul_f32_e32 v17, 0x3fb8aa3b, v17
	v_exp_f32_e32 v22, v17
	v_sub_f32_e32 v17, v45, v117
	v_min_f32_e32 v17, 0x42a00000, v17
	v_mul_f32_e32 v17, 0x3fb8aa3b, v17
	v_exp_f32_e32 v23, v17
	s_waitcnt lgkmcnt(0)
	v_pk_mul_f32 v[22:23], v[118:119], v[22:23]
	s_nop 0
	v_cvt_pk_bf16_f32 v21, v22, v23
	s_nop 1
	v_mfma_f32_16x16x32_bf16 v[20:23], v[18:21], v[0:3], v[12:15]
	s_waitcnt lgkmcnt(0)
	v_mov_b32_e32 v52, v118
	v_mov_b32_e32 v53, v119
	s_and_saveexec_b64 s[2:3], vcc
	v_cmp_gt_u32_e32 vcc, v30, v26
	s_nop 5
	v_cndmask_b32_e64 v12, v20, 0, vcc
	v_cmp_lt_u32_e32 vcc, v30, v26
	s_nop 1
	v_cndmask_b32_e32 v20, v12, v20, vcc
	v_cndmask_b32_e32 v21, 0, v21, vcc
	v_cmp_le_u32_e32 vcc, v50, v26
	s_nop 1
	v_cndmask_b32_e32 v22, 0, v22, vcc
	v_cmp_le_u32_e32 vcc, v49, v26
	s_nop 1
	v_cndmask_b32_e32 v23, 0, v23, vcc
	s_or_b64 exec, exec, s[2:3]
.LBB0_282:
	s_or_b64 exec, exec, s[4:5]
	v_cmp_lt_u32_e32 vcc, 1, v27
	v_mov_b32_e32 v17, 0
	v_mov_b32_e32 v18, 0
	v_mov_b32_e32 v19, 0
	s_and_saveexec_b64 s[4:5], vcc
	s_cbranch_execz .LBB0_286
	s_movk_i32 s2, 0x41
	v_mad_u32_u24 v12, v48, s2, v29
	v_lshl_add_u32 v19, v12, 2, v28
	ds_read2_b32 v[80:81], v19 offset1:1
	v_add_u32_e32 v84, 0x4400, v19
	ds_read2_b32 v[82:83], v84 offset1:1
	ds_read2_b32 v[86:87], v19 offset0:2 offset1:3
	v_add_u32_e32 v85, 0x4408, v19
	ds_read2_b32 v[88:89], v85 offset1:1
	ds_read2_b32 v[90:91], v19 offset0:4 offset1:5
	v_add_u32_e32 v94, 0x4410, v19
	ds_read2_b32 v[92:93], v94 offset1:1
	ds_read2_b32 v[96:97], v19 offset0:6 offset1:7
	v_add_u32_e32 v95, 0x4418, v19
	ds_read2_b32 v[98:99], v95 offset1:1
	ds_read2_b32 v[100:101], v19 offset0:32 offset1:33
	v_add_u32_e32 v104, 0x4480, v19
	ds_read2_b32 v[102:103], v104 offset1:1
	ds_read2_b32 v[106:107], v19 offset0:34 offset1:35
	v_add_u32_e32 v105, 0x4488, v19
	ds_read2_b32 v[108:109], v105 offset1:1
	ds_read2_b32 v[110:111], v19 offset0:36 offset1:37
	v_add_u32_e32 v114, 0x4490, v19
	ds_read2_b32 v[112:113], v114 offset1:1
	ds_read2_b32 v[116:117], v19 offset0:38 offset1:39
	v_add_u32_e32 v115, 0x4498, v19
	ds_read2_b32 v[118:119], v115 offset1:1
	v_add_u32_e32 v14, 0x4400, v19
	v_add_u32_e32 v18, 0x4480, v19
	v_cmp_eq_u32_e64 s[36:37], 2, v27
	s_waitcnt lgkmcnt(1)
	v_sub_f32_e32 v12, v33, v80
	v_sub_f32_e32 v13, v32, v81
	v_min_f32_e32 v12, 0x42a00000, v12
	v_min_f32_e32 v13, 0x42a00000, v13
	v_mul_f32_e32 v12, 0x3fb8aa3b, v12
	v_mul_f32_e32 v13, 0x3fb8aa3b, v13
	v_exp_f32_e32 v12, v12
	v_exp_f32_e32 v13, v13
	s_waitcnt lgkmcnt(0)
	v_pk_mul_f32 v[12:13], v[82:83], v[12:13]
	v_cvt_pk_bf16_f32 v12, v12, v13
	v_add_u32_e32 v13, 0x4408, v19
	s_waitcnt lgkmcnt(1)
	v_sub_f32_e32 v14, v38, v86
	v_sub_f32_e32 v15, v36, v87
	v_min_f32_e32 v14, 0x42a00000, v14
	v_min_f32_e32 v15, 0x42a00000, v15
	v_mul_f32_e32 v14, 0x3fb8aa3b, v14
	v_mul_f32_e32 v15, 0x3fb8aa3b, v15
	v_exp_f32_e32 v14, v14
	v_exp_f32_e32 v15, v15
	s_waitcnt lgkmcnt(0)
	v_pk_mul_f32 v[14:15], v[88:89], v[14:15]
	s_nop 0
	v_cvt_pk_bf16_f32 v13, v14, v15
	v_add_u32_e32 v16, 0x4410, v19
	s_waitcnt lgkmcnt(1)
	v_sub_f32_e32 v14, v42, v90
	v_sub_f32_e32 v15, v39, v91
	v_min_f32_e32 v14, 0x42a00000, v14
	v_min_f32_e32 v15, 0x42a00000, v15
	v_mul_f32_e32 v14, 0x3fb8aa3b, v14
	v_mul_f32_e32 v15, 0x3fb8aa3b, v15
	v_exp_f32_e32 v14, v14
	v_exp_f32_e32 v15, v15
	s_waitcnt lgkmcnt(0)
	v_pk_mul_f32 v[14:15], v[92:93], v[14:15]
	v_cvt_pk_bf16_f32 v14, v14, v15
	v_add_u32_e32 v15, 0x4418, v19
	s_waitcnt lgkmcnt(1)
	v_sub_f32_e32 v16, v46, v96
	v_sub_f32_e32 v17, v44, v97
	v_min_f32_e32 v16, 0x42a00000, v16
	v_min_f32_e32 v17, 0x42a00000, v17
	v_mul_f32_e32 v16, 0x3fb8aa3b, v16
	v_mul_f32_e32 v17, 0x3fb8aa3b, v17
	v_exp_f32_e32 v16, v16
	v_exp_f32_e32 v17, v17
	s_waitcnt lgkmcnt(0)
	v_pk_mul_f32 v[16:17], v[98:99], v[16:17]
	s_nop 0
	v_cvt_pk_bf16_f32 v15, v16, v17
	s_nop 1
	v_mfma_f32_16x16x32_bf16 v[12:15], v[12:15], v[4:7], 0
	s_waitcnt lgkmcnt(1)
	v_sub_f32_e32 v16, v35, v100
	v_sub_f32_e32 v17, v34, v101
	v_min_f32_e32 v16, 0x42a00000, v16
	v_min_f32_e32 v17, 0x42a00000, v17
	v_mul_f32_e32 v16, 0x3fb8aa3b, v16
	v_mul_f32_e32 v17, 0x3fb8aa3b, v17
	v_exp_f32_e32 v16, v16
	v_exp_f32_e32 v17, v17
	s_waitcnt lgkmcnt(0)
	v_pk_mul_f32 v[16:17], v[102:103], v[16:17]
	v_cvt_pk_bf16_f32 v16, v16, v17
	v_add_u32_e32 v17, 0x4488, v19
	s_waitcnt lgkmcnt(1)
	v_sub_f32_e32 v18, v40, v106
	v_min_f32_e32 v18, 0x42a00000, v18
	v_mul_f32_e32 v18, 0x3fb8aa3b, v18
	v_exp_f32_e32 v52, v18
	v_sub_f32_e32 v18, v37, v107
	v_min_f32_e32 v18, 0x42a00000, v18
	v_mul_f32_e32 v18, 0x3fb8aa3b, v18
	v_exp_f32_e32 v53, v18
	v_add_u32_e32 v18, 0x4490, v19
	s_waitcnt lgkmcnt(0)
	v_pk_mul_f32 v[52:53], v[108:109], v[52:53]
	s_nop 0
	v_cvt_pk_bf16_f32 v17, v52, v53
	s_waitcnt lgkmcnt(1)
	v_sub_f32_e32 v48, v43, v110
	v_min_f32_e32 v48, 0x42a00000, v48
	v_mul_f32_e32 v48, 0x3fb8aa3b, v48
	v_exp_f32_e32 v52, v48
	v_sub_f32_e32 v48, v41, v111
	v_min_f32_e32 v48, 0x42a00000, v48
	v_mul_f32_e32 v48, 0x3fb8aa3b, v48
	v_exp_f32_e32 v53, v48
	v_add_u32_e32 v48, 0x4498, v19
	s_waitcnt lgkmcnt(0)
	v_pk_mul_f32 v[52:53], v[112:113], v[52:53]
	s_nop 0
	v_cvt_pk_bf16_f32 v18, v52, v53
	s_waitcnt lgkmcnt(1)
	v_sub_f32_e32 v19, v47, v116
	v_min_f32_e32 v19, 0x42a00000, v19
	v_mul_f32_e32 v19, 0x3fb8aa3b, v19
	v_exp_f32_e32 v52, v19
	v_sub_f32_e32 v19, v45, v117
	v_min_f32_e32 v19, 0x42a00000, v19
	v_mul_f32_e32 v19, 0x3fb8aa3b, v19
	v_exp_f32_e32 v53, v19
	s_waitcnt lgkmcnt(0)
	v_pk_mul_f32 v[52:53], v[118:119], v[52:53]
	s_nop 0
	v_cvt_pk_bf16_f32 v19, v52, v53
	s_nop 1
	v_mfma_f32_16x16x32_bf16 v[16:19], v[16:19], v[0:3], v[12:15]
	s_waitcnt lgkmcnt(0)
	v_mov_b32_e32 v54, v118
	v_mov_b32_e32 v55, v119
	s_and_saveexec_b64 s[2:3], s[36:37]
	v_cmp_gt_u32_e64 s[36:37], v30, v26
	s_nop 5
	v_cndmask_b32_e64 v12, v16, 0, s[36:37]
	v_cmp_lt_u32_e64 s[36:37], v30, v26
	s_nop 1
	v_cndmask_b32_e64 v16, v12, v16, s[36:37]
	v_cndmask_b32_e64 v17, 0, v17, s[36:37]
	v_cmp_le_u32_e64 s[36:37], v50, v26
	s_nop 1
	v_cndmask_b32_e64 v18, 0, v18, s[36:37]
	v_cmp_le_u32_e64 s[36:37], v49, v26
	s_nop 1
	v_cndmask_b32_e64 v19, 0, v19, s[36:37]
	s_or_b64 exec, exec, s[2:3]
.LBB0_286:
	s_or_b64 exec, exec, s[4:5]
	v_cmp_eq_u32_e64 s[36:37], 3, v27
	v_mov_b32_e32 v12, 0
	v_mov_b32_e32 v13, 0
	v_mov_b32_e32 v14, 0
	v_mov_b32_e32 v15, 0
	s_and_saveexec_b64 s[2:3], s[36:37]
	s_cbranch_execz .LBB0_288
	s_movk_i32 s4, 0x41
	v_mad_u32_u24 v12, v31, s4, v29
	v_lshl_add_u32 v27, v12, 2, v28
	ds_read2_b32 v[80:81], v27 offset1:1
	ds_read2_b32 v[82:83], v27 offset0:2 offset1:3
	ds_read2_b32 v[84:85], v27 offset0:4 offset1:5
	ds_read2_b32 v[86:87], v27 offset0:6 offset1:7
	v_add_u32_e32 v90, 0x4400, v27
	ds_read2_b32 v[88:89], v90 offset1:1
	v_add_u32_e32 v91, 0x4408, v27
	ds_read2_b32 v[92:93], v91 offset1:1
	v_add_u32_e32 v96, 0x4410, v27
	ds_read2_b32 v[94:95], v96 offset1:1
	v_add_u32_e32 v97, 0x4418, v27
	ds_read2_b32 v[98:99], v97 offset1:1
	ds_read2_b32 v[100:101], v27 offset0:32 offset1:33
	ds_read2_b32 v[102:103], v27 offset0:34 offset1:35
	ds_read2_b32 v[104:105], v27 offset0:36 offset1:37
	ds_read2_b32 v[106:107], v27 offset0:38 offset1:39
	v_add_u32_e32 v110, 0x4480, v27
	ds_read2_b32 v[108:109], v110 offset1:1
	v_add_u32_e32 v111, 0x4488, v27
	ds_read2_b32 v[112:113], v111 offset1:1
	v_add_u32_e32 v116, 0x4490, v27
	ds_read2_b32 v[114:115], v116 offset1:1
	v_add_u32_e32 v117, 0x4498, v27
	ds_read2_b32 v[118:119], v117 offset1:1
	v_add_u32_e32 v31, 0x4400, v27
	v_cmp_lt_u32_e64 s[36:37], v30, v26
	s_waitcnt lgkmcnt(2)
	v_sub_f32_e32 v14, v38, v82
	v_sub_f32_e32 v12, v33, v80
	v_sub_f32_e32 v13, v32, v81
	v_min_f32_e32 v12, 0x42a00000, v12
	v_min_f32_e32 v13, 0x42a00000, v13
	v_mul_f32_e32 v12, 0x3fb8aa3b, v12
	v_mul_f32_e32 v13, 0x3fb8aa3b, v13
	v_exp_f32_e32 v12, v12
	v_exp_f32_e32 v13, v13
	v_add_u32_e32 v31, 0x4408, v27
	v_sub_f32_e32 v15, v36, v83
	v_add_u32_e32 v38, 0x4418, v27
	s_waitcnt lgkmcnt(0)
	v_pk_mul_f32 v[12:13], v[88:89], v[12:13]
	v_min_f32_e32 v14, 0x42a00000, v14
	v_cvt_pk_bf16_f32 v12, v12, v13
	v_sub_f32_e32 v13, v42, v84
	v_min_f32_e32 v13, 0x42a00000, v13
	v_mul_f32_e32 v13, 0x3fb8aa3b, v13
	v_exp_f32_e32 v32, v13
	v_sub_f32_e32 v13, v39, v85
	v_min_f32_e32 v13, 0x42a00000, v13
	v_mul_f32_e32 v13, 0x3fb8aa3b, v13
	v_exp_f32_e32 v33, v13
	v_sub_f32_e32 v13, v46, v86
	v_min_f32_e32 v13, 0x42a00000, v13
	v_mul_f32_e32 v13, 0x3fb8aa3b, v13
	v_min_f32_e32 v15, 0x42a00000, v15
	v_add_u32_e32 v36, 0x4410, v27
	v_exp_f32_e32 v38, v13
	v_sub_f32_e32 v13, v44, v87
	v_mul_f32_e32 v14, 0x3fb8aa3b, v14
	v_mul_f32_e32 v15, 0x3fb8aa3b, v15
	v_min_f32_e32 v13, 0x42a00000, v13
	v_exp_f32_e32 v14, v14
	v_exp_f32_e32 v15, v15
	v_mul_f32_e32 v13, 0x3fb8aa3b, v13
	v_exp_f32_e32 v39, v13
	v_add_u32_e32 v31, 0x4480, v27
	s_waitcnt lgkmcnt(2)
	v_pk_mul_f32 v[14:15], v[92:93], v[14:15]
	s_nop 0
	v_cvt_pk_bf16_f32 v13, v14, v15
	s_waitcnt lgkmcnt(1)
	v_pk_mul_f32 v[14:15], v[94:95], v[32:33]
	s_waitcnt lgkmcnt(0)
	v_pk_mul_f32 v[32:33], v[98:99], v[38:39]
	v_cvt_pk_bf16_f32 v14, v14, v15
	v_cvt_pk_bf16_f32 v15, v32, v33
	s_nop 1
	v_mfma_f32_16x16x32_bf16 v[4:7], v[12:15], v[4:7], 0
	s_waitcnt lgkmcnt(2)
	v_sub_f32_e32 v14, v40, v102
	v_sub_f32_e32 v12, v35, v100
	v_sub_f32_e32 v13, v34, v101
	v_min_f32_e32 v12, 0x42a00000, v12
	v_min_f32_e32 v13, 0x42a00000, v13
	v_mul_f32_e32 v12, 0x3fb8aa3b, v12
	v_mul_f32_e32 v13, 0x3fb8aa3b, v13
	v_exp_f32_e32 v12, v12
	v_exp_f32_e32 v13, v13
	v_sub_f32_e32 v15, v37, v103
	v_min_f32_e32 v14, 0x42a00000, v14
	v_min_f32_e32 v15, 0x42a00000, v15
	s_waitcnt lgkmcnt(0)
	v_pk_mul_f32 v[12:13], v[108:109], v[12:13]
	v_add_u32_e32 v31, 0x4488, v27
	v_cvt_pk_bf16_f32 v12, v12, v13
	v_sub_f32_e32 v13, v43, v104
	v_min_f32_e32 v13, 0x42a00000, v13
	v_mul_f32_e32 v13, 0x3fb8aa3b, v13
	v_exp_f32_e32 v32, v13
	v_sub_f32_e32 v13, v41, v105
	v_min_f32_e32 v13, 0x42a00000, v13
	v_mul_f32_e32 v13, 0x3fb8aa3b, v13
	v_exp_f32_e32 v33, v13
	v_sub_f32_e32 v13, v47, v106
	v_min_f32_e32 v13, 0x42a00000, v13
	v_mul_f32_e32 v13, 0x3fb8aa3b, v13
	v_exp_f32_e32 v34, v13
	v_sub_f32_e32 v13, v45, v107
	v_mul_f32_e32 v14, 0x3fb8aa3b, v14
	v_mul_f32_e32 v15, 0x3fb8aa3b, v15
	v_min_f32_e32 v13, 0x42a00000, v13
	v_exp_f32_e32 v14, v14
	v_exp_f32_e32 v15, v15
	v_add_u32_e32 v40, 0x4490, v27
	v_add_u32_e32 v27, 0x4498, v27
	v_mul_f32_e32 v13, 0x3fb8aa3b, v13
	v_exp_f32_e32 v35, v13
	s_waitcnt lgkmcnt(2)
	v_pk_mul_f32 v[14:15], v[112:113], v[14:15]
	s_nop 0
	v_cvt_pk_bf16_f32 v13, v14, v15
	s_waitcnt lgkmcnt(1)
	v_pk_mul_f32 v[14:15], v[114:115], v[32:33]
	s_waitcnt lgkmcnt(0)
	v_pk_mul_f32 v[32:33], v[118:119], v[34:35]
	v_cvt_pk_bf16_f32 v14, v14, v15
	v_cvt_pk_bf16_f32 v15, v32, v33
	s_nop 1
	v_mfma_f32_16x16x32_bf16 v[0:3], v[12:15], v[0:3], v[4:7]
	s_nop 7
	v_cndmask_b32_e64 v13, 0, v1, s[36:37]
	v_cmp_le_u32_e64 s[36:37], v30, v26
	s_nop 1
	v_cndmask_b32_e64 v12, 0, v0, s[36:37]
	v_cmp_le_u32_e64 s[36:37], v50, v26
	s_nop 1
	v_cndmask_b32_e64 v14, 0, v2, s[36:37]
	v_cmp_le_u32_e64 s[36:37], v49, v26
	s_nop 1
	v_cndmask_b32_e64 v15, 0, v3, s[36:37]
	s_waitcnt lgkmcnt(0)
	v_mov_b32_e32 v36, v112
	v_mov_b32_e32 v37, v113
	v_mov_b32_e32 v38, v106
	v_mov_b32_e32 v39, v107
	v_mov_b32_e32 v52, v114
	v_mov_b32_e32 v53, v115
	v_mov_b32_e32 v54, v118
	v_mov_b32_e32 v55, v119
	v_mov_b32_e32 v56, v92
	v_mov_b32_e32 v57, v93
	v_mov_b32_e32 v58, v94
	v_mov_b32_e32 v59, v95
	v_mov_b32_e32 v60, v98
	v_mov_b32_e32 v61, v99
.LBB0_288:
	s_or_b64 exec, exec, s[2:3]
	v_mul_u32_u24_e32 v0, 0x90, v26
	v_add_u32_e32 v1, v28, v29
	v_add_u32_e32 v28, v1, v0
	v_add_u32_e32 v29, 0x8800, v28
	v_add_u32_e32 v26, 0x9000, v28
	v_add_u32_e32 v27, 0x9800, v28
	v_add_u32_e32 v28, 0xa000, v28
	ds_read2_b64 v[80:83], v29 offset1:4
	ds_read2_b64 v[84:87], v26 offset0:32 offset1:36
	ds_read2_b64 v[88:91], v27 offset0:64 offset1:68
	ds_read2_b64 v[92:95], v28 offset0:96 offset1:100
	v_cvt_pk_bf16_f32 v32, v8, v9
	v_cvt_pk_bf16_f32 v33, v10, v11
	v_cvt_pk_bf16_f32 v34, v20, v21
	v_cvt_pk_bf16_f32 v35, v22, v23
	s_waitcnt lgkmcnt(3)
	s_nop 0
	v_mfma_f32_16x16x32_bf16 v[0:3], v[80:83], v[32:35], 0
	s_waitcnt lgkmcnt(2)
	v_mfma_f32_16x16x32_bf16 v[4:7], v[84:87], v[32:35], 0
	s_waitcnt lgkmcnt(1)
	v_mfma_f32_16x16x32_bf16 v[8:11], v[88:91], v[32:35], 0
	s_waitcnt lgkmcnt(0)
	v_mfma_f32_16x16x32_bf16 v[20:23], v[92:95], v[32:35], 0
	s_and_saveexec_b64 s[2:3], vcc
	s_cbranch_execz .LBB0_290
	v_cvt_pk_bf16_f32 v16, v16, v17
	v_cvt_pk_bf16_f32 v17, v18, v19
	v_cvt_pk_bf16_f32 v18, v12, v13
	v_cvt_pk_bf16_f32 v19, v14, v15
	ds_read2_b64 v[80:83], v29 offset0:8 offset1:12
	ds_read2_b64 v[84:87], v26 offset0:40 offset1:44
	ds_read2_b64 v[88:91], v27 offset0:72 offset1:76
	ds_read2_b64 v[92:95], v28 offset0:104 offset1:108
	s_waitcnt lgkmcnt(0)
	v_mfma_f32_16x16x32_bf16 v[0:3], v[80:83], v[16:19], v[0:3]
	s_waitcnt lgkmcnt(0)
	v_mfma_f32_16x16x32_bf16 v[4:7], v[84:87], v[16:19], v[4:7]
	s_waitcnt lgkmcnt(0)
	v_mfma_f32_16x16x32_bf16 v[8:11], v[88:91], v[16:19], v[8:11]
	s_waitcnt lgkmcnt(0)
	v_mfma_f32_16x16x32_bf16 v[20:23], v[92:95], v[16:19], v[20:23]
	s_waitcnt lgkmcnt(0)
	v_mov_b32_e32 v12, v92
	v_mov_b32_e32 v13, v93
	v_mov_b32_e32 v14, v94
	v_mov_b32_e32 v15, v95
